# K-loop: LDS-DMA loads issued ahead of the ds_reads in all four load phases (phases 1 and 3 use v252-v253 addresses; next_free_vgpr 256)
# baseline (speedup 1.0000x reference)
.LBB0_511:
	s_add_i32 s62, s30, 2
	s_add_u32 s63, s28, 0x80
	s_addc_u32 s31, s29, 0
	s_add_i32 s66, 0, 0x10000
	s_cmp_eq_u32 s54, s30
	s_cselect_b32 s31, s7, s31
	s_cselect_b32 s30, s6, s63
	v_add_u32_e32 v156, s66, v141
	s_cselect_b32 s65, s27, s61
	s_cselect_b32 s64, s26, s60
	s_add_i32 s63, 0, 0x14000
	v_lshl_add_u64 v[252:253], s[28:29], 0, v[136:137]
	s_add_i32 m0, s47, 0xc000
	s_nop 0
	global_load_lds_dwordx4 v[252:253], off
	v_lshl_add_u64 v[252:253], s[28:29], 0, v[138:139]
	s_add_i32 m0, s47, 0xe000
	s_nop 0
	global_load_lds_dwordx4 v[252:253], off
	ds_read_b128 v[144:147], v156
	ds_read_b128 v[148:151], v156 offset:1024
	ds_read_b128 v[152:155], v156 offset:2048
	ds_read_b128 v[160:163], v156 offset:3072
	v_add_u32_e32 v156, s63, v141
	ds_read_b128 v[164:167], v156
	ds_read_b128 v[168:171], v156 offset:1024
	ds_read_b128 v[172:175], v156 offset:2048
	ds_read_b128 v[176:179], v156 offset:3072
	ds_read_b128 v[180:183], v143
	ds_read_b128 v[184:187], v143 offset:1024
	ds_read_b128 v[188:191], v143 offset:2048
	ds_read_b128 v[192:195], v143 offset:3072
	ds_read_b128 v[214:217], v143 offset:4096
	ds_read_b128 v[218:221], v143 offset:5120
	ds_read_b128 v[222:225], v143 offset:6144
	ds_read_b128 v[226:229], v143 offset:7168
	s_waitcnt vmcnt(8)
	s_waitcnt lgkmcnt(0)
	s_barrier
	s_setprio 1
	s_waitcnt lgkmcnt(0)
	v_mfma_f32_16x16x32_bf16 v[122:125], v[144:147], v[180:183], v[122:125]
	v_mfma_f32_16x16x32_bf16 v[118:121], v[152:155], v[180:183], v[118:121]
	v_mfma_f32_16x16x32_bf16 v[110:113], v[144:147], v[188:191], v[110:113]
	v_mfma_f32_16x16x32_bf16 v[102:105], v[152:155], v[188:191], v[102:105]
	v_mfma_f32_16x16x32_bf16 v[94:97], v[144:147], v[214:217], v[94:97]
	v_mfma_f32_16x16x32_bf16 v[84:87], v[152:155], v[214:217], v[84:87]
	v_mfma_f32_16x16x32_bf16 v[76:79], v[144:147], v[222:225], v[76:79]
	v_mfma_f32_16x16x32_bf16 v[68:71], v[152:155], v[222:225], v[68:71]
	v_mfma_f32_16x16x32_bf16 v[122:125], v[148:151], v[184:187], v[122:125]
	v_mfma_f32_16x16x32_bf16 v[118:121], v[160:163], v[184:187], v[118:121]
	v_mfma_f32_16x16x32_bf16 v[110:113], v[148:151], v[192:195], v[110:113]
	v_mfma_f32_16x16x32_bf16 v[102:105], v[160:163], v[192:195], v[102:105]
	v_mfma_f32_16x16x32_bf16 v[94:97], v[148:151], v[218:221], v[94:97]
	v_mfma_f32_16x16x32_bf16 v[84:87], v[160:163], v[218:221], v[84:87]
	v_mfma_f32_16x16x32_bf16 v[76:79], v[148:151], v[226:229], v[76:79]
	v_mfma_f32_16x16x32_bf16 v[68:71], v[160:163], v[226:229], v[68:71]
	s_setprio 0
	s_setprio 1
	v_mfma_f32_16x16x32_bf16 v[126:129], v[164:167], v[180:183], v[126:129]
	v_mfma_f32_16x16x32_bf16 v[114:117], v[172:175], v[180:183], v[114:117]
	v_mfma_f32_16x16x32_bf16 v[106:109], v[164:167], v[188:191], v[106:109]
	v_mfma_f32_16x16x32_bf16 v[98:101], v[172:175], v[188:191], v[98:101]
	v_mfma_f32_16x16x32_bf16 v[88:91], v[164:167], v[214:217], v[88:91]
	v_mfma_f32_16x16x32_bf16 v[80:83], v[172:175], v[214:217], v[80:83]
	v_mfma_f32_16x16x32_bf16 v[72:75], v[164:167], v[222:225], v[72:75]
	v_mfma_f32_16x16x32_bf16 v[64:67], v[172:175], v[222:225], v[64:67]
	v_mfma_f32_16x16x32_bf16 v[126:129], v[168:171], v[184:187], v[126:129]
	v_mfma_f32_16x16x32_bf16 v[114:117], v[176:179], v[184:187], v[114:117]
	v_mfma_f32_16x16x32_bf16 v[106:109], v[168:171], v[192:195], v[106:109]
	v_mfma_f32_16x16x32_bf16 v[98:101], v[176:179], v[192:195], v[98:101]
	v_mfma_f32_16x16x32_bf16 v[88:91], v[168:171], v[218:221], v[88:91]
	v_mfma_f32_16x16x32_bf16 v[80:83], v[176:179], v[218:221], v[80:83]
	v_mfma_f32_16x16x32_bf16 v[72:75], v[168:171], v[226:229], v[72:75]
	v_mfma_f32_16x16x32_bf16 v[64:67], v[176:179], v[226:229], v[64:67]
	s_setprio 0
	s_barrier
	s_add_i32 s66, s66, s44
	v_lshl_add_u64 v[156:157], s[64:65], 0, v[92:93]
	s_mov_b32 m0, s66
	s_nop 0
	global_load_lds_dwordx4 v[156:157], off
	s_add_i32 m0, s66, 0x2000
	v_lshl_add_u64 v[230:231], s[64:65], 0, v[134:135]
	s_add_u32 s64, s64, s10
	s_addc_u32 s65, s65, s11
	s_add_i32 s63, s63, s44
	global_load_lds_dwordx4 v[230:231], off
	v_lshl_add_u64 v[232:233], s[64:65], 0, v[92:93]
	s_mov_b32 m0, s63
	v_lshl_add_u64 v[234:235], s[64:65], 0, v[134:135]
	global_load_lds_dwordx4 v[232:233], off
	s_add_i32 m0, s63, 0x2000
	v_lshl_add_u64 v[236:237], s[30:31], 0, v[130:131]
	global_load_lds_dwordx4 v[234:235], off
	s_mov_b32 m0, s47
	v_lshl_add_u64 v[238:239], s[30:31], 0, v[132:133]
	global_load_lds_dwordx4 v[236:237], off
	s_mov_b32 m0, s48
	s_nop 0
	global_load_lds_dwordx4 v[238:239], off
	ds_read_b128 v[180:183], v143 offset:16384
	ds_read_b128 v[184:187], v143 offset:17408
	ds_read_b128 v[188:191], v143 offset:18432
	ds_read_b128 v[192:195], v143 offset:19456
	ds_read_b128 v[214:217], v143 offset:20480
	ds_read_b128 v[218:221], v143 offset:21504
	ds_read_b128 v[222:225], v143 offset:22528
	ds_read_b128 v[226:229], v143 offset:23552
	s_waitcnt vmcnt(8)
	s_waitcnt lgkmcnt(0)
	s_barrier
	s_setprio 1
	s_waitcnt lgkmcnt(0)
	v_mfma_f32_16x16x32_bf16 v[60:63], v[144:147], v[180:183], v[60:63]
	v_mfma_f32_16x16x32_bf16 v[52:55], v[152:155], v[180:183], v[52:55]
	v_mfma_f32_16x16x32_bf16 v[44:47], v[144:147], v[188:191], v[44:47]
	v_mfma_f32_16x16x32_bf16 v[36:39], v[152:155], v[188:191], v[36:39]
	v_mfma_f32_16x16x32_bf16 v[28:31], v[144:147], v[214:217], v[28:31]
	v_mfma_f32_16x16x32_bf16 v[20:23], v[152:155], v[214:217], v[20:23]
	v_mfma_f32_16x16x32_bf16 v[12:15], v[144:147], v[222:225], v[12:15]
	v_mfma_f32_16x16x32_bf16 v[4:7], v[152:155], v[222:225], v[4:7]
	v_mfma_f32_16x16x32_bf16 v[60:63], v[148:151], v[184:187], v[60:63]
	v_mfma_f32_16x16x32_bf16 v[52:55], v[160:163], v[184:187], v[52:55]
	v_mfma_f32_16x16x32_bf16 v[44:47], v[148:151], v[192:195], v[44:47]
	v_mfma_f32_16x16x32_bf16 v[36:39], v[160:163], v[192:195], v[36:39]
	v_mfma_f32_16x16x32_bf16 v[28:31], v[148:151], v[218:221], v[28:31]
	v_mfma_f32_16x16x32_bf16 v[20:23], v[160:163], v[218:221], v[20:23]
	v_mfma_f32_16x16x32_bf16 v[12:15], v[148:151], v[226:229], v[12:15]
	v_mfma_f32_16x16x32_bf16 v[4:7], v[160:163], v[226:229], v[4:7]
	s_setprio 0
	s_setprio 1
	v_mfma_f32_16x16x32_bf16 v[56:59], v[164:167], v[180:183], v[56:59]
	v_mfma_f32_16x16x32_bf16 v[48:51], v[172:175], v[180:183], v[48:51]
	v_mfma_f32_16x16x32_bf16 v[40:43], v[164:167], v[188:191], v[40:43]
	v_mfma_f32_16x16x32_bf16 v[32:35], v[172:175], v[188:191], v[32:35]
	v_mfma_f32_16x16x32_bf16 v[24:27], v[164:167], v[214:217], v[24:27]
	v_mfma_f32_16x16x32_bf16 v[16:19], v[172:175], v[214:217], v[16:19]
	v_mfma_f32_16x16x32_bf16 v[8:11], v[164:167], v[222:225], v[8:11]
	v_mfma_f32_16x16x32_bf16 v[0:3], v[172:175], v[222:225], v[0:3]
	v_mfma_f32_16x16x32_bf16 v[56:59], v[168:171], v[184:187], v[56:59]
	v_mfma_f32_16x16x32_bf16 v[48:51], v[176:179], v[184:187], v[48:51]
	v_mfma_f32_16x16x32_bf16 v[40:43], v[168:171], v[192:195], v[40:43]
	v_mfma_f32_16x16x32_bf16 v[32:35], v[176:179], v[192:195], v[32:35]
	v_mfma_f32_16x16x32_bf16 v[24:27], v[168:171], v[218:221], v[24:27]
	v_mfma_f32_16x16x32_bf16 v[16:19], v[176:179], v[218:221], v[16:19]
	v_mfma_f32_16x16x32_bf16 v[8:11], v[168:171], v[226:229], v[8:11]
	v_mfma_f32_16x16x32_bf16 v[0:3], v[176:179], v[226:229], v[0:3]
	s_setprio 0
	s_barrier
	s_add_i32 s63, 0, 0x18000
	v_add_u32_e32 v159, s63, v141
	s_add_i32 s64, 0, 0x1c000
	s_add_u32 s30, s30, s14
	s_addc_u32 s31, s31, s15
	s_mov_b32 m0, s49
	v_lshl_add_u64 v[240:241], s[30:31], 0, v[130:131]
	global_load_lds_dwordx4 v[240:241], off
	v_lshl_add_u64 v[240:241], s[30:31], 0, v[132:133]
	s_mov_b32 m0, s50
	s_nop 0
	global_load_lds_dwordx4 v[240:241], off
	ds_read_b128 v[144:147], v159
	ds_read_b128 v[148:151], v159 offset:1024
	ds_read_b128 v[152:155], v159 offset:2048
	ds_read_b128 v[160:163], v159 offset:3072
	v_add_u32_e32 v159, s64, v141
	ds_read_b128 v[164:167], v159
	ds_read_b128 v[168:171], v159 offset:1024
	ds_read_b128 v[172:175], v159 offset:2048
	ds_read_b128 v[176:179], v159 offset:3072
	ds_read_b128 v[180:183], v143 offset:32768
	ds_read_b128 v[184:187], v143 offset:33792
	ds_read_b128 v[188:191], v143 offset:34816
	ds_read_b128 v[192:195], v143 offset:35840
	ds_read_b128 v[214:217], v143 offset:36864
	ds_read_b128 v[218:221], v143 offset:37888
	ds_read_b128 v[222:225], v143 offset:38912
	ds_read_b128 v[226:229], v143 offset:39936
	s_waitcnt vmcnt(8)
	s_waitcnt lgkmcnt(0)
	s_barrier
	s_setprio 1
	s_waitcnt lgkmcnt(0)
	v_mfma_f32_16x16x32_bf16 v[122:125], v[144:147], v[180:183], v[122:125]
	v_mfma_f32_16x16x32_bf16 v[118:121], v[152:155], v[180:183], v[118:121]
	v_mfma_f32_16x16x32_bf16 v[110:113], v[144:147], v[188:191], v[110:113]
	v_mfma_f32_16x16x32_bf16 v[102:105], v[152:155], v[188:191], v[102:105]
	v_mfma_f32_16x16x32_bf16 v[94:97], v[144:147], v[214:217], v[94:97]
	v_mfma_f32_16x16x32_bf16 v[84:87], v[152:155], v[214:217], v[84:87]
	v_mfma_f32_16x16x32_bf16 v[76:79], v[144:147], v[222:225], v[76:79]
	v_mfma_f32_16x16x32_bf16 v[68:71], v[152:155], v[222:225], v[68:71]
	v_mfma_f32_16x16x32_bf16 v[122:125], v[148:151], v[184:187], v[122:125]
	v_mfma_f32_16x16x32_bf16 v[118:121], v[160:163], v[184:187], v[118:121]
	v_mfma_f32_16x16x32_bf16 v[110:113], v[148:151], v[192:195], v[110:113]
	v_mfma_f32_16x16x32_bf16 v[102:105], v[160:163], v[192:195], v[102:105]
	v_mfma_f32_16x16x32_bf16 v[94:97], v[148:151], v[218:221], v[94:97]
	v_mfma_f32_16x16x32_bf16 v[84:87], v[160:163], v[218:221], v[84:87]
	v_mfma_f32_16x16x32_bf16 v[76:79], v[148:151], v[226:229], v[76:79]
	v_mfma_f32_16x16x32_bf16 v[68:71], v[160:163], v[226:229], v[68:71]
	s_setprio 0
	s_setprio 1
	v_mfma_f32_16x16x32_bf16 v[126:129], v[164:167], v[180:183], v[126:129]
	v_mfma_f32_16x16x32_bf16 v[114:117], v[172:175], v[180:183], v[114:117]
	v_mfma_f32_16x16x32_bf16 v[106:109], v[164:167], v[188:191], v[106:109]
	v_mfma_f32_16x16x32_bf16 v[98:101], v[172:175], v[188:191], v[98:101]
	v_mfma_f32_16x16x32_bf16 v[88:91], v[164:167], v[214:217], v[88:91]
	v_mfma_f32_16x16x32_bf16 v[80:83], v[172:175], v[214:217], v[80:83]
	v_mfma_f32_16x16x32_bf16 v[72:75], v[164:167], v[222:225], v[72:75]
	v_mfma_f32_16x16x32_bf16 v[64:67], v[172:175], v[222:225], v[64:67]
	v_mfma_f32_16x16x32_bf16 v[126:129], v[168:171], v[184:187], v[126:129]
	v_mfma_f32_16x16x32_bf16 v[114:117], v[176:179], v[184:187], v[114:117]
	v_mfma_f32_16x16x32_bf16 v[106:109], v[168:171], v[192:195], v[106:109]
	v_mfma_f32_16x16x32_bf16 v[98:101], v[176:179], v[192:195], v[98:101]
	v_mfma_f32_16x16x32_bf16 v[88:91], v[168:171], v[218:221], v[88:91]
	v_mfma_f32_16x16x32_bf16 v[80:83], v[176:179], v[218:221], v[80:83]
	v_mfma_f32_16x16x32_bf16 v[72:75], v[168:171], v[226:229], v[72:75]
	v_mfma_f32_16x16x32_bf16 v[64:67], v[176:179], v[226:229], v[64:67]
	s_setprio 0
	s_barrier
	s_add_i32 s30, s63, s44
	v_lshl_add_u64 v[156:157], v[156:157], 0, s[80:81]
	s_mov_b32 m0, s30
	s_nop 0
	global_load_lds_dwordx4 v[156:157], off
	v_lshl_add_u64 v[156:157], v[230:231], 0, s[80:81]
	s_add_i32 m0, s30, 0x2000
	s_add_i32 s30, s64, s44
	global_load_lds_dwordx4 v[156:157], off
	v_lshl_add_u64 v[156:157], v[232:233], 0, s[80:81]
	s_mov_b32 m0, s30
	s_nop 0
	global_load_lds_dwordx4 v[156:157], off
	v_lshl_add_u64 v[156:157], v[234:235], 0, s[80:81]
	s_add_i32 m0, s30, 0x2000
	s_nop 0
	global_load_lds_dwordx4 v[156:157], off
	v_lshl_add_u64 v[156:157], v[236:237], 0, s[80:81]
	s_mov_b32 m0, s51
	s_nop 0
	global_load_lds_dwordx4 v[156:157], off
	v_lshl_add_u64 v[156:157], v[238:239], 0, s[80:81]
	s_mov_b32 m0, s52
	s_nop 0
	global_load_lds_dwordx4 v[156:157], off
	ds_read_b128 v[180:183], v143 offset:49152
	ds_read_b128 v[184:187], v143 offset:50176
	ds_read_b128 v[188:191], v143 offset:51200
	ds_read_b128 v[192:195], v143 offset:52224
	ds_read_b128 v[214:217], v143 offset:53248
	ds_read_b128 v[218:221], v143 offset:54272
	ds_read_b128 v[222:225], v143 offset:55296
	ds_read_b128 v[226:229], v143 offset:56320
	s_waitcnt vmcnt(8)
	s_waitcnt lgkmcnt(0)
	s_barrier
	s_setprio 1
	s_waitcnt lgkmcnt(0)
	v_mfma_f32_16x16x32_bf16 v[60:63], v[144:147], v[180:183], v[60:63]
	v_mfma_f32_16x16x32_bf16 v[52:55], v[152:155], v[180:183], v[52:55]
	v_mfma_f32_16x16x32_bf16 v[44:47], v[144:147], v[188:191], v[44:47]
	v_mfma_f32_16x16x32_bf16 v[36:39], v[152:155], v[188:191], v[36:39]
	v_mfma_f32_16x16x32_bf16 v[28:31], v[144:147], v[214:217], v[28:31]
	v_mfma_f32_16x16x32_bf16 v[20:23], v[152:155], v[214:217], v[20:23]
	v_mfma_f32_16x16x32_bf16 v[12:15], v[144:147], v[222:225], v[12:15]
	v_mfma_f32_16x16x32_bf16 v[4:7], v[152:155], v[222:225], v[4:7]
	v_mfma_f32_16x16x32_bf16 v[60:63], v[148:151], v[184:187], v[60:63]
	v_mfma_f32_16x16x32_bf16 v[52:55], v[160:163], v[184:187], v[52:55]
	v_mfma_f32_16x16x32_bf16 v[44:47], v[148:151], v[192:195], v[44:47]
	v_mfma_f32_16x16x32_bf16 v[36:39], v[160:163], v[192:195], v[36:39]
	v_mfma_f32_16x16x32_bf16 v[28:31], v[148:151], v[218:221], v[28:31]
	v_mfma_f32_16x16x32_bf16 v[20:23], v[160:163], v[218:221], v[20:23]
	v_mfma_f32_16x16x32_bf16 v[12:15], v[148:151], v[226:229], v[12:15]
	v_mfma_f32_16x16x32_bf16 v[4:7], v[160:163], v[226:229], v[4:7]
	s_setprio 0
	s_setprio 1
	v_mfma_f32_16x16x32_bf16 v[56:59], v[164:167], v[180:183], v[56:59]
	v_mfma_f32_16x16x32_bf16 v[48:51], v[172:175], v[180:183], v[48:51]
	v_mfma_f32_16x16x32_bf16 v[40:43], v[164:167], v[188:191], v[40:43]
	v_mfma_f32_16x16x32_bf16 v[32:35], v[172:175], v[188:191], v[32:35]
	v_mfma_f32_16x16x32_bf16 v[24:27], v[164:167], v[214:217], v[24:27]
	v_mfma_f32_16x16x32_bf16 v[16:19], v[172:175], v[214:217], v[16:19]
	v_mfma_f32_16x16x32_bf16 v[8:11], v[164:167], v[222:225], v[8:11]
	v_mfma_f32_16x16x32_bf16 v[0:3], v[172:175], v[222:225], v[0:3]
	v_mfma_f32_16x16x32_bf16 v[56:59], v[168:171], v[184:187], v[56:59]
	v_mfma_f32_16x16x32_bf16 v[48:51], v[176:179], v[184:187], v[48:51]
	v_mfma_f32_16x16x32_bf16 v[40:43], v[168:171], v[192:195], v[40:43]
	v_mfma_f32_16x16x32_bf16 v[32:35], v[176:179], v[192:195], v[32:35]
	v_mfma_f32_16x16x32_bf16 v[24:27], v[168:171], v[218:221], v[24:27]
	v_mfma_f32_16x16x32_bf16 v[16:19], v[176:179], v[218:221], v[16:19]
	v_mfma_f32_16x16x32_bf16 v[8:11], v[168:171], v[226:229], v[8:11]
	v_mfma_f32_16x16x32_bf16 v[0:3], v[176:179], v[226:229], v[0:3]
	s_setprio 0
	s_barrier
	s_add_u32 s28, s28, 0x100
	s_addc_u32 s29, s29, 0
	s_add_u32 s60, s60, 0x100
	s_addc_u32 s61, s61, 0
	s_cmp_ge_i32 s62, s53
	s_mov_b32 s30, s62
	s_cbranch_scc0 .LBB0_511

.LBB0_596:
	s_add_i32 s63, s30, 2
	s_add_u32 s64, s28, 0x80
	s_addc_u32 s31, s29, 0
	s_add_i32 s66, 0, 0x10000
	s_cmp_eq_u32 s55, s30
	s_cselect_b32 s31, s7, s31
	s_cselect_b32 s30, s6, s64
	s_cselect_b32 s65, s27, s62
	s_cselect_b32 s64, s26, s61
	s_add_i32 s67, 0, 0x14000
	v_add_u32_e32 v152, s66, v164
	v_add_u32_e32 v156, s67, v164
	v_lshl_add_u64 v[252:253], s[28:29], 0, v[136:137]
	s_add_i32 m0, s46, 0xc000
	s_nop 0
	global_load_lds_dwordx4 v[252:253], off
	v_lshl_add_u64 v[252:253], s[28:29], 0, v[138:139]
	s_add_i32 m0, s46, 0xe000
	s_nop 0
	global_load_lds_dwordx4 v[252:253], off
	ds_read_b128 v[140:143], v152
	ds_read_b128 v[144:147], v152 offset:1024
	ds_read_b128 v[148:151], v152 offset:2048
	ds_read_b128 v[152:155], v152 offset:3072
	ds_read_b128 v[160:163], v156
	ds_read_b128 v[168:171], v156 offset:1024
	ds_read_b128 v[172:175], v156 offset:2048
	ds_read_b128 v[176:179], v156 offset:3072
	ds_read_b128 v[180:183], v166
	ds_read_b128 v[184:187], v166 offset:1024
	ds_read_b128 v[188:191], v166 offset:2048
	ds_read_b128 v[192:195], v166 offset:3072
	ds_read_b128 v[214:217], v166 offset:4096
	ds_read_b128 v[218:221], v166 offset:5120
	ds_read_b128 v[222:225], v166 offset:6144
	ds_read_b128 v[226:229], v166 offset:7168
	s_waitcnt vmcnt(8)
	s_waitcnt lgkmcnt(0)
	s_barrier
	s_setprio 1
	s_waitcnt lgkmcnt(0)
	v_mfma_f32_16x16x32_bf16 v[126:129], v[140:143], v[180:183], v[126:129]
	v_mfma_f32_16x16x32_bf16 v[122:125], v[148:151], v[180:183], v[122:125]
	v_mfma_f32_16x16x32_bf16 v[110:113], v[140:143], v[188:191], v[110:113]
	v_mfma_f32_16x16x32_bf16 v[106:109], v[148:151], v[188:191], v[106:109]
	v_mfma_f32_16x16x32_bf16 v[94:97], v[140:143], v[214:217], v[94:97]
	v_mfma_f32_16x16x32_bf16 v[88:91], v[148:151], v[214:217], v[88:91]
	v_mfma_f32_16x16x32_bf16 v[76:79], v[140:143], v[222:225], v[76:79]
	v_mfma_f32_16x16x32_bf16 v[72:75], v[148:151], v[222:225], v[72:75]
	v_mfma_f32_16x16x32_bf16 v[126:129], v[144:147], v[184:187], v[126:129]
	v_mfma_f32_16x16x32_bf16 v[122:125], v[152:155], v[184:187], v[122:125]
	v_mfma_f32_16x16x32_bf16 v[110:113], v[144:147], v[192:195], v[110:113]
	v_mfma_f32_16x16x32_bf16 v[106:109], v[152:155], v[192:195], v[106:109]
	v_mfma_f32_16x16x32_bf16 v[94:97], v[144:147], v[218:221], v[94:97]
	v_mfma_f32_16x16x32_bf16 v[88:91], v[152:155], v[218:221], v[88:91]
	v_mfma_f32_16x16x32_bf16 v[76:79], v[144:147], v[226:229], v[76:79]
	v_mfma_f32_16x16x32_bf16 v[72:75], v[152:155], v[226:229], v[72:75]
	s_setprio 0
	s_setprio 1
	v_mfma_f32_16x16x32_bf16 v[118:121], v[160:163], v[180:183], v[118:121]
	v_mfma_f32_16x16x32_bf16 v[114:117], v[172:175], v[180:183], v[114:117]
	v_mfma_f32_16x16x32_bf16 v[102:105], v[160:163], v[188:191], v[102:105]
	v_mfma_f32_16x16x32_bf16 v[98:101], v[172:175], v[188:191], v[98:101]
	v_mfma_f32_16x16x32_bf16 v[84:87], v[160:163], v[214:217], v[84:87]
	v_mfma_f32_16x16x32_bf16 v[80:83], v[172:175], v[214:217], v[80:83]
	v_mfma_f32_16x16x32_bf16 v[68:71], v[160:163], v[222:225], v[68:71]
	v_mfma_f32_16x16x32_bf16 v[64:67], v[172:175], v[222:225], v[64:67]
	v_mfma_f32_16x16x32_bf16 v[118:121], v[168:171], v[184:187], v[118:121]
	v_mfma_f32_16x16x32_bf16 v[114:117], v[176:179], v[184:187], v[114:117]
	v_mfma_f32_16x16x32_bf16 v[102:105], v[168:171], v[192:195], v[102:105]
	v_mfma_f32_16x16x32_bf16 v[98:101], v[176:179], v[192:195], v[98:101]
	v_mfma_f32_16x16x32_bf16 v[84:87], v[168:171], v[218:221], v[84:87]
	v_mfma_f32_16x16x32_bf16 v[80:83], v[176:179], v[218:221], v[80:83]
	v_mfma_f32_16x16x32_bf16 v[68:71], v[168:171], v[226:229], v[68:71]
	v_mfma_f32_16x16x32_bf16 v[64:67], v[176:179], v[226:229], v[64:67]
	s_setprio 0
	s_barrier
	s_add_i32 s66, s66, s41
	v_lshl_add_u64 v[156:157], s[64:65], 0, v[92:93]
	s_mov_b32 m0, s66
	s_nop 0
	global_load_lds_dwordx4 v[156:157], off
	s_add_i32 m0, s66, 0x2000
	v_lshl_add_u64 v[230:231], s[64:65], 0, v[134:135]
	s_add_u32 s64, s64, s10
	s_addc_u32 s65, s65, s11
	s_add_i32 s66, s67, s41
	global_load_lds_dwordx4 v[230:231], off
	v_lshl_add_u64 v[232:233], s[64:65], 0, v[92:93]
	s_mov_b32 m0, s66
	v_lshl_add_u64 v[234:235], s[64:65], 0, v[134:135]
	global_load_lds_dwordx4 v[232:233], off
	s_add_i32 m0, s66, 0x2000
	v_lshl_add_u64 v[236:237], s[30:31], 0, v[130:131]
	global_load_lds_dwordx4 v[234:235], off
	s_mov_b32 m0, s46
	v_lshl_add_u64 v[238:239], s[30:31], 0, v[132:133]
	global_load_lds_dwordx4 v[236:237], off
	s_mov_b32 m0, s47
	s_nop 0
	global_load_lds_dwordx4 v[238:239], off
	ds_read_b128 v[180:183], v166 offset:16384
	ds_read_b128 v[184:187], v166 offset:17408
	ds_read_b128 v[188:191], v166 offset:18432
	ds_read_b128 v[192:195], v166 offset:19456
	ds_read_b128 v[214:217], v166 offset:20480
	ds_read_b128 v[218:221], v166 offset:21504
	ds_read_b128 v[222:225], v166 offset:22528
	ds_read_b128 v[226:229], v166 offset:23552
	s_waitcnt vmcnt(8)
	s_waitcnt lgkmcnt(0)
	s_barrier
	s_setprio 1
	s_waitcnt lgkmcnt(0)
	v_mfma_f32_16x16x32_bf16 v[60:63], v[140:143], v[180:183], v[60:63]
	v_mfma_f32_16x16x32_bf16 v[56:59], v[148:151], v[180:183], v[56:59]
	v_mfma_f32_16x16x32_bf16 v[44:47], v[140:143], v[188:191], v[44:47]
	v_mfma_f32_16x16x32_bf16 v[40:43], v[148:151], v[188:191], v[40:43]
	v_mfma_f32_16x16x32_bf16 v[28:31], v[140:143], v[214:217], v[28:31]
	v_mfma_f32_16x16x32_bf16 v[24:27], v[148:151], v[214:217], v[24:27]
	v_mfma_f32_16x16x32_bf16 v[12:15], v[140:143], v[222:225], v[12:15]
	v_mfma_f32_16x16x32_bf16 v[8:11], v[148:151], v[222:225], v[8:11]
	v_mfma_f32_16x16x32_bf16 v[60:63], v[144:147], v[184:187], v[60:63]
	v_mfma_f32_16x16x32_bf16 v[56:59], v[152:155], v[184:187], v[56:59]
	v_mfma_f32_16x16x32_bf16 v[44:47], v[144:147], v[192:195], v[44:47]
	v_mfma_f32_16x16x32_bf16 v[40:43], v[152:155], v[192:195], v[40:43]
	v_mfma_f32_16x16x32_bf16 v[28:31], v[144:147], v[218:221], v[28:31]
	v_mfma_f32_16x16x32_bf16 v[24:27], v[152:155], v[218:221], v[24:27]
	v_mfma_f32_16x16x32_bf16 v[12:15], v[144:147], v[226:229], v[12:15]
	v_mfma_f32_16x16x32_bf16 v[8:11], v[152:155], v[226:229], v[8:11]
	s_setprio 0
	s_setprio 1
	v_mfma_f32_16x16x32_bf16 v[52:55], v[160:163], v[180:183], v[52:55]
	v_mfma_f32_16x16x32_bf16 v[48:51], v[172:175], v[180:183], v[48:51]
	v_mfma_f32_16x16x32_bf16 v[36:39], v[160:163], v[188:191], v[36:39]
	v_mfma_f32_16x16x32_bf16 v[32:35], v[172:175], v[188:191], v[32:35]
	v_mfma_f32_16x16x32_bf16 v[20:23], v[160:163], v[214:217], v[20:23]
	v_mfma_f32_16x16x32_bf16 v[16:19], v[172:175], v[214:217], v[16:19]
	v_mfma_f32_16x16x32_bf16 v[4:7], v[160:163], v[222:225], v[4:7]
	v_mfma_f32_16x16x32_bf16 v[0:3], v[172:175], v[222:225], v[0:3]
	v_mfma_f32_16x16x32_bf16 v[52:55], v[168:171], v[184:187], v[52:55]
	v_mfma_f32_16x16x32_bf16 v[48:51], v[176:179], v[184:187], v[48:51]
	v_mfma_f32_16x16x32_bf16 v[36:39], v[168:171], v[192:195], v[36:39]
	v_mfma_f32_16x16x32_bf16 v[32:35], v[176:179], v[192:195], v[32:35]
	v_mfma_f32_16x16x32_bf16 v[20:23], v[168:171], v[218:221], v[20:23]
	v_mfma_f32_16x16x32_bf16 v[16:19], v[176:179], v[218:221], v[16:19]
	v_mfma_f32_16x16x32_bf16 v[4:7], v[168:171], v[226:229], v[4:7]
	v_mfma_f32_16x16x32_bf16 v[0:3], v[176:179], v[226:229], v[0:3]
	s_setprio 0
	s_barrier
	s_add_i32 s64, 0, 0x18000
	s_add_i32 s65, 0, 0x1c000
	v_add_u32_e32 v152, s64, v164
	v_add_u32_e32 v167, s65, v164
	s_add_u32 s30, s30, s14
	s_addc_u32 s31, s31, s15
	s_mov_b32 m0, s48
	v_lshl_add_u64 v[240:241], s[30:31], 0, v[130:131]
	global_load_lds_dwordx4 v[240:241], off
	v_lshl_add_u64 v[240:241], s[30:31], 0, v[132:133]
	s_mov_b32 m0, s49
	s_nop 0
	global_load_lds_dwordx4 v[240:241], off
	ds_read_b128 v[140:143], v152
	ds_read_b128 v[144:147], v152 offset:1024
	ds_read_b128 v[148:151], v152 offset:2048
	ds_read_b128 v[152:155], v152 offset:3072
	ds_read_b128 v[160:163], v167
	ds_read_b128 v[168:171], v167 offset:1024
	ds_read_b128 v[172:175], v167 offset:2048
	ds_read_b128 v[176:179], v167 offset:3072
	ds_read_b128 v[180:183], v166 offset:32768
	ds_read_b128 v[184:187], v166 offset:33792
	ds_read_b128 v[188:191], v166 offset:34816
	ds_read_b128 v[192:195], v166 offset:35840
	ds_read_b128 v[214:217], v166 offset:36864
	ds_read_b128 v[218:221], v166 offset:37888
	ds_read_b128 v[222:225], v166 offset:38912
	ds_read_b128 v[226:229], v166 offset:39936
	s_waitcnt vmcnt(8)
	s_waitcnt lgkmcnt(0)
	s_barrier
	s_setprio 1
	s_waitcnt lgkmcnt(0)
	v_mfma_f32_16x16x32_bf16 v[126:129], v[140:143], v[180:183], v[126:129]
	v_mfma_f32_16x16x32_bf16 v[122:125], v[148:151], v[180:183], v[122:125]
	v_mfma_f32_16x16x32_bf16 v[110:113], v[140:143], v[188:191], v[110:113]
	v_mfma_f32_16x16x32_bf16 v[106:109], v[148:151], v[188:191], v[106:109]
	v_mfma_f32_16x16x32_bf16 v[94:97], v[140:143], v[214:217], v[94:97]
	v_mfma_f32_16x16x32_bf16 v[88:91], v[148:151], v[214:217], v[88:91]
	v_mfma_f32_16x16x32_bf16 v[76:79], v[140:143], v[222:225], v[76:79]
	v_mfma_f32_16x16x32_bf16 v[72:75], v[148:151], v[222:225], v[72:75]
	v_mfma_f32_16x16x32_bf16 v[126:129], v[144:147], v[184:187], v[126:129]
	v_mfma_f32_16x16x32_bf16 v[122:125], v[152:155], v[184:187], v[122:125]
	v_mfma_f32_16x16x32_bf16 v[110:113], v[144:147], v[192:195], v[110:113]
	v_mfma_f32_16x16x32_bf16 v[106:109], v[152:155], v[192:195], v[106:109]
	v_mfma_f32_16x16x32_bf16 v[94:97], v[144:147], v[218:221], v[94:97]
	v_mfma_f32_16x16x32_bf16 v[88:91], v[152:155], v[218:221], v[88:91]
	v_mfma_f32_16x16x32_bf16 v[76:79], v[144:147], v[226:229], v[76:79]
	v_mfma_f32_16x16x32_bf16 v[72:75], v[152:155], v[226:229], v[72:75]
	s_setprio 0
	s_setprio 1
	v_mfma_f32_16x16x32_bf16 v[118:121], v[160:163], v[180:183], v[118:121]
	v_mfma_f32_16x16x32_bf16 v[114:117], v[172:175], v[180:183], v[114:117]
	v_mfma_f32_16x16x32_bf16 v[102:105], v[160:163], v[188:191], v[102:105]
	v_mfma_f32_16x16x32_bf16 v[98:101], v[172:175], v[188:191], v[98:101]
	v_mfma_f32_16x16x32_bf16 v[84:87], v[160:163], v[214:217], v[84:87]
	v_mfma_f32_16x16x32_bf16 v[80:83], v[172:175], v[214:217], v[80:83]
	v_mfma_f32_16x16x32_bf16 v[68:71], v[160:163], v[222:225], v[68:71]
	v_mfma_f32_16x16x32_bf16 v[64:67], v[172:175], v[222:225], v[64:67]
	v_mfma_f32_16x16x32_bf16 v[118:121], v[168:171], v[184:187], v[118:121]
	v_mfma_f32_16x16x32_bf16 v[114:117], v[176:179], v[184:187], v[114:117]
	v_mfma_f32_16x16x32_bf16 v[102:105], v[168:171], v[192:195], v[102:105]
	v_mfma_f32_16x16x32_bf16 v[98:101], v[176:179], v[192:195], v[98:101]
	v_mfma_f32_16x16x32_bf16 v[84:87], v[168:171], v[218:221], v[84:87]
	v_mfma_f32_16x16x32_bf16 v[80:83], v[176:179], v[218:221], v[80:83]
	v_mfma_f32_16x16x32_bf16 v[68:71], v[168:171], v[226:229], v[68:71]
	v_mfma_f32_16x16x32_bf16 v[64:67], v[176:179], v[226:229], v[64:67]
	s_setprio 0
	s_barrier
	s_add_i32 s30, s64, s41
	v_lshl_add_u64 v[156:157], v[156:157], 0, s[80:81]
	s_mov_b32 m0, s30
	s_nop 0
	global_load_lds_dwordx4 v[156:157], off
	v_lshl_add_u64 v[156:157], v[230:231], 0, s[80:81]
	s_add_i32 m0, s30, 0x2000
	s_add_i32 s30, s65, s41
	global_load_lds_dwordx4 v[156:157], off
	v_lshl_add_u64 v[156:157], v[232:233], 0, s[80:81]
	s_mov_b32 m0, s30
	s_nop 0
	global_load_lds_dwordx4 v[156:157], off
	v_lshl_add_u64 v[156:157], v[234:235], 0, s[80:81]
	s_add_i32 m0, s30, 0x2000
	s_nop 0
	global_load_lds_dwordx4 v[156:157], off
	v_lshl_add_u64 v[156:157], v[236:237], 0, s[80:81]
	s_mov_b32 m0, s53
	s_nop 0
	global_load_lds_dwordx4 v[156:157], off
	v_lshl_add_u64 v[156:157], v[238:239], 0, s[80:81]
	s_mov_b32 m0, s54
	s_nop 0
	global_load_lds_dwordx4 v[156:157], off
	ds_read_b128 v[180:183], v166 offset:49152
	ds_read_b128 v[184:187], v166 offset:50176
	ds_read_b128 v[188:191], v166 offset:51200
	ds_read_b128 v[192:195], v166 offset:52224
	ds_read_b128 v[214:217], v166 offset:53248
	ds_read_b128 v[218:221], v166 offset:54272
	ds_read_b128 v[222:225], v166 offset:55296
	ds_read_b128 v[226:229], v166 offset:56320
	s_waitcnt vmcnt(8)
	s_waitcnt lgkmcnt(0)
	s_barrier
	s_setprio 1
	s_waitcnt lgkmcnt(0)
	v_mfma_f32_16x16x32_bf16 v[60:63], v[140:143], v[180:183], v[60:63]
	v_mfma_f32_16x16x32_bf16 v[56:59], v[148:151], v[180:183], v[56:59]
	v_mfma_f32_16x16x32_bf16 v[44:47], v[140:143], v[188:191], v[44:47]
	v_mfma_f32_16x16x32_bf16 v[40:43], v[148:151], v[188:191], v[40:43]
	v_mfma_f32_16x16x32_bf16 v[28:31], v[140:143], v[214:217], v[28:31]
	v_mfma_f32_16x16x32_bf16 v[24:27], v[148:151], v[214:217], v[24:27]
	v_mfma_f32_16x16x32_bf16 v[12:15], v[140:143], v[222:225], v[12:15]
	v_mfma_f32_16x16x32_bf16 v[8:11], v[148:151], v[222:225], v[8:11]
	v_mfma_f32_16x16x32_bf16 v[60:63], v[144:147], v[184:187], v[60:63]
	v_mfma_f32_16x16x32_bf16 v[56:59], v[152:155], v[184:187], v[56:59]
	v_mfma_f32_16x16x32_bf16 v[44:47], v[144:147], v[192:195], v[44:47]
	v_mfma_f32_16x16x32_bf16 v[40:43], v[152:155], v[192:195], v[40:43]
	v_mfma_f32_16x16x32_bf16 v[28:31], v[144:147], v[218:221], v[28:31]
	v_mfma_f32_16x16x32_bf16 v[24:27], v[152:155], v[218:221], v[24:27]
	v_mfma_f32_16x16x32_bf16 v[12:15], v[144:147], v[226:229], v[12:15]
	v_mfma_f32_16x16x32_bf16 v[8:11], v[152:155], v[226:229], v[8:11]
	s_setprio 0
	s_setprio 1
	v_mfma_f32_16x16x32_bf16 v[52:55], v[160:163], v[180:183], v[52:55]
	v_mfma_f32_16x16x32_bf16 v[48:51], v[172:175], v[180:183], v[48:51]
	v_mfma_f32_16x16x32_bf16 v[36:39], v[160:163], v[188:191], v[36:39]
	v_mfma_f32_16x16x32_bf16 v[32:35], v[172:175], v[188:191], v[32:35]
	v_mfma_f32_16x16x32_bf16 v[20:23], v[160:163], v[214:217], v[20:23]
	v_mfma_f32_16x16x32_bf16 v[16:19], v[172:175], v[214:217], v[16:19]
	v_mfma_f32_16x16x32_bf16 v[4:7], v[160:163], v[222:225], v[4:7]
	v_mfma_f32_16x16x32_bf16 v[0:3], v[172:175], v[222:225], v[0:3]
	v_mfma_f32_16x16x32_bf16 v[52:55], v[168:171], v[184:187], v[52:55]
	v_mfma_f32_16x16x32_bf16 v[48:51], v[176:179], v[184:187], v[48:51]
	v_mfma_f32_16x16x32_bf16 v[36:39], v[168:171], v[192:195], v[36:39]
	v_mfma_f32_16x16x32_bf16 v[32:35], v[176:179], v[192:195], v[32:35]
	v_mfma_f32_16x16x32_bf16 v[20:23], v[168:171], v[218:221], v[20:23]
	v_mfma_f32_16x16x32_bf16 v[16:19], v[176:179], v[218:221], v[16:19]
	v_mfma_f32_16x16x32_bf16 v[4:7], v[168:171], v[226:229], v[4:7]
	v_mfma_f32_16x16x32_bf16 v[0:3], v[176:179], v[226:229], v[0:3]
	s_setprio 0
	s_barrier
	s_add_u32 s28, s28, 0x100
	s_addc_u32 s29, s29, 0
	s_add_u32 s61, s61, 0x100
	s_addc_u32 s62, s62, 0
	s_cmp_ge_i32 s63, s52
	s_mov_b32 s30, s63
	s_cbranch_scc0 .LBB0_596
	s_movk_i32 s67, 0x4000

.LBB0_685:
	s_add_i32 s36, s10, 2
	s_add_u32 s37, s8, 0x80
	s_addc_u32 s11, s9, 0
	s_add_i32 s40, 0, 0x10000
	s_cmp_eq_u32 s71, s10
	s_cselect_b32 s11, s29, s11
	s_cselect_b32 s10, s28, s37
	v_add_u32_e32 v92, s40, v141
	s_cselect_b32 s39, s31, s35
	s_cselect_b32 s38, s30, s34
	s_add_i32 s37, 0, 0x14000
	v_lshl_add_u64 v[156:157], s[8:9], 0, v[148:149]
	s_add_i32 m0, s54, 0xc000
	s_nop 0
	global_load_lds_dwordx4 v[156:157], off
	v_lshl_add_u64 v[156:157], s[8:9], 0, v[150:151]
	s_add_i32 m0, s54, 0xe000
	s_nop 0
	global_load_lds_dwordx4 v[156:157], off
	ds_read_b128 v[152:155], v92
	ds_read_b128 v[160:163], v92 offset:1024
	ds_read_b128 v[164:167], v92 offset:2048
	ds_read_b128 v[168:171], v92 offset:3072
	v_add_u32_e32 v92, s37, v141
	ds_read_b128 v[172:175], v92
	ds_read_b128 v[176:179], v92 offset:1024
	ds_read_b128 v[180:183], v92 offset:2048
	ds_read_b128 v[184:187], v92 offset:3072
	ds_read_b128 v[188:191], v143
	ds_read_b128 v[192:195], v143 offset:1024
	ds_read_b128 v[214:217], v143 offset:2048
	ds_read_b128 v[218:221], v143 offset:3072
	ds_read_b128 v[222:225], v143 offset:4096
	ds_read_b128 v[226:229], v143 offset:5120
	ds_read_b128 v[230:233], v143 offset:6144
	ds_read_b128 v[234:237], v143 offset:7168
	s_waitcnt vmcnt(8)
	s_waitcnt lgkmcnt(0)
	s_barrier
	s_setprio 1
	s_waitcnt lgkmcnt(0)
	v_mfma_f32_16x16x32_bf16 v[126:129], v[152:155], v[188:191], v[126:129]
	v_mfma_f32_16x16x32_bf16 v[122:125], v[164:167], v[188:191], v[122:125]
	v_mfma_f32_16x16x32_bf16 v[118:121], v[152:155], v[214:217], v[118:121]
	v_mfma_f32_16x16x32_bf16 v[114:117], v[164:167], v[214:217], v[114:117]
	v_mfma_f32_16x16x32_bf16 v[110:113], v[152:155], v[222:225], v[110:113]
	v_mfma_f32_16x16x32_bf16 v[106:109], v[164:167], v[222:225], v[106:109]
	v_mfma_f32_16x16x32_bf16 v[102:105], v[152:155], v[230:233], v[102:105]
	v_mfma_f32_16x16x32_bf16 v[98:101], v[164:167], v[230:233], v[98:101]
	v_mfma_f32_16x16x32_bf16 v[126:129], v[160:163], v[192:195], v[126:129]
	v_mfma_f32_16x16x32_bf16 v[122:125], v[168:171], v[192:195], v[122:125]
	v_mfma_f32_16x16x32_bf16 v[118:121], v[160:163], v[218:221], v[118:121]
	v_mfma_f32_16x16x32_bf16 v[114:117], v[168:171], v[218:221], v[114:117]
	v_mfma_f32_16x16x32_bf16 v[110:113], v[160:163], v[226:229], v[110:113]
	v_mfma_f32_16x16x32_bf16 v[106:109], v[168:171], v[226:229], v[106:109]
	v_mfma_f32_16x16x32_bf16 v[102:105], v[160:163], v[234:237], v[102:105]
	v_mfma_f32_16x16x32_bf16 v[98:101], v[168:171], v[234:237], v[98:101]
	s_setprio 0
	s_setprio 1
	v_mfma_f32_16x16x32_bf16 v[60:63], v[172:175], v[188:191], v[60:63]
	v_mfma_f32_16x16x32_bf16 v[56:59], v[180:183], v[188:191], v[56:59]
	v_mfma_f32_16x16x32_bf16 v[52:55], v[172:175], v[214:217], v[52:55]
	v_mfma_f32_16x16x32_bf16 v[48:51], v[180:183], v[214:217], v[48:51]
	v_mfma_f32_16x16x32_bf16 v[44:47], v[172:175], v[222:225], v[44:47]
	v_mfma_f32_16x16x32_bf16 v[40:43], v[180:183], v[222:225], v[40:43]
	v_mfma_f32_16x16x32_bf16 v[36:39], v[172:175], v[230:233], v[36:39]
	v_mfma_f32_16x16x32_bf16 v[32:35], v[180:183], v[230:233], v[32:35]
	v_mfma_f32_16x16x32_bf16 v[60:63], v[176:179], v[192:195], v[60:63]
	v_mfma_f32_16x16x32_bf16 v[56:59], v[184:187], v[192:195], v[56:59]
	v_mfma_f32_16x16x32_bf16 v[52:55], v[176:179], v[218:221], v[52:55]
	v_mfma_f32_16x16x32_bf16 v[48:51], v[184:187], v[218:221], v[48:51]
	v_mfma_f32_16x16x32_bf16 v[44:47], v[176:179], v[226:229], v[44:47]
	v_mfma_f32_16x16x32_bf16 v[40:43], v[184:187], v[226:229], v[40:43]
	v_mfma_f32_16x16x32_bf16 v[36:39], v[176:179], v[234:237], v[36:39]
	v_mfma_f32_16x16x32_bf16 v[32:35], v[184:187], v[234:237], v[32:35]
	s_setprio 0
	s_barrier
	s_add_i32 s40, s40, s53
	v_lshl_add_u64 v[156:157], s[38:39], 0, v[132:133]
	s_mov_b32 m0, s40
	s_nop 0
	global_load_lds_dwordx4 v[156:157], off
	s_add_i32 m0, s40, 0x2000
	v_lshl_add_u64 v[238:239], s[38:39], 0, v[136:137]
	s_add_u32 s38, s38, s12
	s_addc_u32 s39, s39, s13
	s_add_i32 s37, s37, s53
	global_load_lds_dwordx4 v[238:239], off
	v_lshl_add_u64 v[240:241], s[38:39], 0, v[132:133]
	s_mov_b32 m0, s37
	v_lshl_add_u64 v[242:243], s[38:39], 0, v[136:137]
	global_load_lds_dwordx4 v[240:241], off
	s_add_i32 m0, s37, 0x2000
	v_lshl_add_u64 v[244:245], s[10:11], 0, v[130:131]
	global_load_lds_dwordx4 v[242:243], off
	s_mov_b32 m0, s54
	v_lshl_add_u64 v[246:247], s[10:11], 0, v[134:135]
	global_load_lds_dwordx4 v[244:245], off
	s_mov_b32 m0, s55
	s_nop 0
	global_load_lds_dwordx4 v[246:247], off
	ds_read_b128 v[188:191], v143 offset:16384
	ds_read_b128 v[192:195], v143 offset:17408
	ds_read_b128 v[214:217], v143 offset:18432
	ds_read_b128 v[218:221], v143 offset:19456
	ds_read_b128 v[222:225], v143 offset:20480
	ds_read_b128 v[226:229], v143 offset:21504
	ds_read_b128 v[230:233], v143 offset:22528
	ds_read_b128 v[234:237], v143 offset:23552
	s_waitcnt vmcnt(8)
	s_waitcnt lgkmcnt(0)
	s_barrier
	s_setprio 1
	s_waitcnt lgkmcnt(0)
	v_mfma_f32_16x16x32_bf16 v[94:97], v[152:155], v[188:191], v[94:97]
	v_mfma_f32_16x16x32_bf16 v[88:91], v[164:167], v[188:191], v[88:91]
	v_mfma_f32_16x16x32_bf16 v[84:87], v[152:155], v[214:217], v[84:87]
	v_mfma_f32_16x16x32_bf16 v[80:83], v[164:167], v[214:217], v[80:83]
	v_mfma_f32_16x16x32_bf16 v[76:79], v[152:155], v[222:225], v[76:79]
	v_mfma_f32_16x16x32_bf16 v[72:75], v[164:167], v[222:225], v[72:75]
	v_mfma_f32_16x16x32_bf16 v[68:71], v[152:155], v[230:233], v[68:71]
	v_mfma_f32_16x16x32_bf16 v[64:67], v[164:167], v[230:233], v[64:67]
	v_mfma_f32_16x16x32_bf16 v[94:97], v[160:163], v[192:195], v[94:97]
	v_mfma_f32_16x16x32_bf16 v[88:91], v[168:171], v[192:195], v[88:91]
	v_mfma_f32_16x16x32_bf16 v[84:87], v[160:163], v[218:221], v[84:87]
	v_mfma_f32_16x16x32_bf16 v[80:83], v[168:171], v[218:221], v[80:83]
	v_mfma_f32_16x16x32_bf16 v[76:79], v[160:163], v[226:229], v[76:79]
	v_mfma_f32_16x16x32_bf16 v[72:75], v[168:171], v[226:229], v[72:75]
	v_mfma_f32_16x16x32_bf16 v[68:71], v[160:163], v[234:237], v[68:71]
	v_mfma_f32_16x16x32_bf16 v[64:67], v[168:171], v[234:237], v[64:67]
	s_setprio 0
	s_setprio 1
	v_mfma_f32_16x16x32_bf16 v[28:31], v[172:175], v[188:191], v[28:31]
	v_mfma_f32_16x16x32_bf16 v[24:27], v[180:183], v[188:191], v[24:27]
	v_mfma_f32_16x16x32_bf16 v[20:23], v[172:175], v[214:217], v[20:23]
	v_mfma_f32_16x16x32_bf16 v[16:19], v[180:183], v[214:217], v[16:19]
	v_mfma_f32_16x16x32_bf16 v[12:15], v[172:175], v[222:225], v[12:15]
	v_mfma_f32_16x16x32_bf16 v[8:11], v[180:183], v[222:225], v[8:11]
	v_mfma_f32_16x16x32_bf16 v[4:7], v[172:175], v[230:233], v[4:7]
	v_mfma_f32_16x16x32_bf16 v[0:3], v[180:183], v[230:233], v[0:3]
	v_mfma_f32_16x16x32_bf16 v[28:31], v[176:179], v[192:195], v[28:31]
	v_mfma_f32_16x16x32_bf16 v[24:27], v[184:187], v[192:195], v[24:27]
	v_mfma_f32_16x16x32_bf16 v[20:23], v[176:179], v[218:221], v[20:23]
	v_mfma_f32_16x16x32_bf16 v[16:19], v[184:187], v[218:221], v[16:19]
	v_mfma_f32_16x16x32_bf16 v[12:15], v[176:179], v[226:229], v[12:15]
	v_mfma_f32_16x16x32_bf16 v[8:11], v[184:187], v[226:229], v[8:11]
	v_mfma_f32_16x16x32_bf16 v[4:7], v[176:179], v[234:237], v[4:7]
	v_mfma_f32_16x16x32_bf16 v[0:3], v[184:187], v[234:237], v[0:3]
	s_setprio 0
	s_barrier
	s_add_i32 s37, 0, 0x18000
	v_add_u32_e32 v92, s37, v141
	s_add_i32 s38, 0, 0x1c000
	s_add_u32 s10, s10, s16
	s_addc_u32 s11, s11, s17
	s_mov_b32 m0, s56
	v_lshl_add_u64 v[248:249], s[10:11], 0, v[130:131]
	global_load_lds_dwordx4 v[248:249], off
	v_lshl_add_u64 v[248:249], s[10:11], 0, v[134:135]
	s_mov_b32 m0, s57
	s_nop 0
	global_load_lds_dwordx4 v[248:249], off
	ds_read_b128 v[152:155], v92
	ds_read_b128 v[160:163], v92 offset:1024
	ds_read_b128 v[164:167], v92 offset:2048
	ds_read_b128 v[168:171], v92 offset:3072
	v_add_u32_e32 v92, s38, v141
	ds_read_b128 v[172:175], v92
	ds_read_b128 v[176:179], v92 offset:1024
	ds_read_b128 v[180:183], v92 offset:2048
	ds_read_b128 v[184:187], v92 offset:3072
	ds_read_b128 v[188:191], v143 offset:32768
	ds_read_b128 v[192:195], v143 offset:33792
	ds_read_b128 v[214:217], v143 offset:34816
	ds_read_b128 v[218:221], v143 offset:35840
	ds_read_b128 v[222:225], v143 offset:36864
	ds_read_b128 v[226:229], v143 offset:37888
	ds_read_b128 v[230:233], v143 offset:38912
	ds_read_b128 v[234:237], v143 offset:39936
	s_waitcnt vmcnt(8)
	s_waitcnt lgkmcnt(0)
	s_barrier
	s_setprio 1
	s_waitcnt lgkmcnt(0)
	v_mfma_f32_16x16x32_bf16 v[126:129], v[152:155], v[188:191], v[126:129]
	v_mfma_f32_16x16x32_bf16 v[122:125], v[164:167], v[188:191], v[122:125]
	v_mfma_f32_16x16x32_bf16 v[118:121], v[152:155], v[214:217], v[118:121]
	v_mfma_f32_16x16x32_bf16 v[114:117], v[164:167], v[214:217], v[114:117]
	v_mfma_f32_16x16x32_bf16 v[110:113], v[152:155], v[222:225], v[110:113]
	v_mfma_f32_16x16x32_bf16 v[106:109], v[164:167], v[222:225], v[106:109]
	v_mfma_f32_16x16x32_bf16 v[102:105], v[152:155], v[230:233], v[102:105]
	v_mfma_f32_16x16x32_bf16 v[98:101], v[164:167], v[230:233], v[98:101]
	v_mfma_f32_16x16x32_bf16 v[126:129], v[160:163], v[192:195], v[126:129]
	v_mfma_f32_16x16x32_bf16 v[122:125], v[168:171], v[192:195], v[122:125]
	v_mfma_f32_16x16x32_bf16 v[118:121], v[160:163], v[218:221], v[118:121]
	v_mfma_f32_16x16x32_bf16 v[114:117], v[168:171], v[218:221], v[114:117]
	v_mfma_f32_16x16x32_bf16 v[110:113], v[160:163], v[226:229], v[110:113]
	v_mfma_f32_16x16x32_bf16 v[106:109], v[168:171], v[226:229], v[106:109]
	v_mfma_f32_16x16x32_bf16 v[102:105], v[160:163], v[234:237], v[102:105]
	v_mfma_f32_16x16x32_bf16 v[98:101], v[168:171], v[234:237], v[98:101]
	s_setprio 0
	s_setprio 1
	v_mfma_f32_16x16x32_bf16 v[60:63], v[172:175], v[188:191], v[60:63]
	v_mfma_f32_16x16x32_bf16 v[56:59], v[180:183], v[188:191], v[56:59]
	v_mfma_f32_16x16x32_bf16 v[52:55], v[172:175], v[214:217], v[52:55]
	v_mfma_f32_16x16x32_bf16 v[48:51], v[180:183], v[214:217], v[48:51]
	v_mfma_f32_16x16x32_bf16 v[44:47], v[172:175], v[222:225], v[44:47]
	v_mfma_f32_16x16x32_bf16 v[40:43], v[180:183], v[222:225], v[40:43]
	v_mfma_f32_16x16x32_bf16 v[36:39], v[172:175], v[230:233], v[36:39]
	v_mfma_f32_16x16x32_bf16 v[32:35], v[180:183], v[230:233], v[32:35]
	v_mfma_f32_16x16x32_bf16 v[60:63], v[176:179], v[192:195], v[60:63]
	v_mfma_f32_16x16x32_bf16 v[56:59], v[184:187], v[192:195], v[56:59]
	v_mfma_f32_16x16x32_bf16 v[52:55], v[176:179], v[218:221], v[52:55]
	v_mfma_f32_16x16x32_bf16 v[48:51], v[184:187], v[218:221], v[48:51]
	v_mfma_f32_16x16x32_bf16 v[44:47], v[176:179], v[226:229], v[44:47]
	v_mfma_f32_16x16x32_bf16 v[40:43], v[184:187], v[226:229], v[40:43]
	v_mfma_f32_16x16x32_bf16 v[36:39], v[176:179], v[234:237], v[36:39]
	v_mfma_f32_16x16x32_bf16 v[32:35], v[184:187], v[234:237], v[32:35]
	s_setprio 0
	s_barrier
	s_add_i32 s10, s37, s53
	v_lshl_add_u64 v[156:157], v[156:157], 0, s[80:81]
	s_mov_b32 m0, s10
	s_nop 0
	global_load_lds_dwordx4 v[156:157], off
	v_lshl_add_u64 v[156:157], v[238:239], 0, s[80:81]
	s_add_i32 m0, s10, 0x2000
	s_add_i32 s10, s38, s53
	global_load_lds_dwordx4 v[156:157], off
	v_lshl_add_u64 v[156:157], v[240:241], 0, s[80:81]
	s_mov_b32 m0, s10
	s_nop 0
	global_load_lds_dwordx4 v[156:157], off
	v_lshl_add_u64 v[156:157], v[242:243], 0, s[80:81]
	s_add_i32 m0, s10, 0x2000
	s_nop 0
	global_load_lds_dwordx4 v[156:157], off
	v_lshl_add_u64 v[156:157], v[244:245], 0, s[80:81]
	s_mov_b32 m0, s69
	s_nop 0
	global_load_lds_dwordx4 v[156:157], off
	v_lshl_add_u64 v[156:157], v[246:247], 0, s[80:81]
	s_mov_b32 m0, s70
	s_nop 0
	global_load_lds_dwordx4 v[156:157], off
	ds_read_b128 v[188:191], v143 offset:49152
	ds_read_b128 v[192:195], v143 offset:50176
	ds_read_b128 v[214:217], v143 offset:51200
	ds_read_b128 v[218:221], v143 offset:52224
	ds_read_b128 v[222:225], v143 offset:53248
	ds_read_b128 v[226:229], v143 offset:54272
	ds_read_b128 v[230:233], v143 offset:55296
	ds_read_b128 v[234:237], v143 offset:56320
	s_waitcnt vmcnt(8)
	s_waitcnt lgkmcnt(0)
	s_barrier
	s_setprio 1
	s_waitcnt lgkmcnt(0)
	v_mfma_f32_16x16x32_bf16 v[94:97], v[152:155], v[188:191], v[94:97]
	v_mfma_f32_16x16x32_bf16 v[88:91], v[164:167], v[188:191], v[88:91]
	v_mfma_f32_16x16x32_bf16 v[84:87], v[152:155], v[214:217], v[84:87]
	v_mfma_f32_16x16x32_bf16 v[80:83], v[164:167], v[214:217], v[80:83]
	v_mfma_f32_16x16x32_bf16 v[76:79], v[152:155], v[222:225], v[76:79]
	v_mfma_f32_16x16x32_bf16 v[72:75], v[164:167], v[222:225], v[72:75]
	v_mfma_f32_16x16x32_bf16 v[68:71], v[152:155], v[230:233], v[68:71]
	v_mfma_f32_16x16x32_bf16 v[64:67], v[164:167], v[230:233], v[64:67]
	v_mfma_f32_16x16x32_bf16 v[94:97], v[160:163], v[192:195], v[94:97]
	v_mfma_f32_16x16x32_bf16 v[88:91], v[168:171], v[192:195], v[88:91]
	v_mfma_f32_16x16x32_bf16 v[84:87], v[160:163], v[218:221], v[84:87]
	v_mfma_f32_16x16x32_bf16 v[80:83], v[168:171], v[218:221], v[80:83]
	v_mfma_f32_16x16x32_bf16 v[76:79], v[160:163], v[226:229], v[76:79]
	v_mfma_f32_16x16x32_bf16 v[72:75], v[168:171], v[226:229], v[72:75]
	v_mfma_f32_16x16x32_bf16 v[68:71], v[160:163], v[234:237], v[68:71]
	v_mfma_f32_16x16x32_bf16 v[64:67], v[168:171], v[234:237], v[64:67]
	s_setprio 0
	s_setprio 1
	v_mfma_f32_16x16x32_bf16 v[28:31], v[172:175], v[188:191], v[28:31]
	v_mfma_f32_16x16x32_bf16 v[24:27], v[180:183], v[188:191], v[24:27]
	v_mfma_f32_16x16x32_bf16 v[20:23], v[172:175], v[214:217], v[20:23]
	v_mfma_f32_16x16x32_bf16 v[16:19], v[180:183], v[214:217], v[16:19]
	v_mfma_f32_16x16x32_bf16 v[12:15], v[172:175], v[222:225], v[12:15]
	v_mfma_f32_16x16x32_bf16 v[8:11], v[180:183], v[222:225], v[8:11]
	v_mfma_f32_16x16x32_bf16 v[4:7], v[172:175], v[230:233], v[4:7]
	v_mfma_f32_16x16x32_bf16 v[0:3], v[180:183], v[230:233], v[0:3]
	v_mfma_f32_16x16x32_bf16 v[28:31], v[176:179], v[192:195], v[28:31]
	v_mfma_f32_16x16x32_bf16 v[24:27], v[184:187], v[192:195], v[24:27]
	v_mfma_f32_16x16x32_bf16 v[20:23], v[176:179], v[218:221], v[20:23]
	v_mfma_f32_16x16x32_bf16 v[16:19], v[184:187], v[218:221], v[16:19]
	v_mfma_f32_16x16x32_bf16 v[12:15], v[176:179], v[226:229], v[12:15]
	v_mfma_f32_16x16x32_bf16 v[8:11], v[184:187], v[226:229], v[8:11]
	v_mfma_f32_16x16x32_bf16 v[4:7], v[176:179], v[234:237], v[4:7]
	v_mfma_f32_16x16x32_bf16 v[0:3], v[184:187], v[234:237], v[0:3]
	s_setprio 0
	s_barrier
	s_add_u32 s8, s8, 0x100
	s_addc_u32 s9, s9, 0
	s_add_u32 s34, s34, 0x100
	s_addc_u32 s35, s35, 0
	s_cmp_ge_i32 s36, s68
	s_mov_b32 s10, s36
	s_cbranch_scc0 .LBB0_685

.LBB0_962:
	s_add_i32 s63, s24, 2
	s_add_u32 s64, s26, 0x80
	s_addc_u32 s25, s27, 0
	s_add_i32 s66, 0, 0x10000
	v_add_u32_e32 v79, s66, v77
	ds_read_b128 v[80:83], v79
	ds_read_b128 v[84:87], v79 offset:1024
	ds_read_b128 v[88:91], v79 offset:2048
	ds_read_b128 v[94:97], v79 offset:3072
	s_cmp_eq_u32 s57, s24
	s_cselect_b32 s24, s6, s64
	s_cselect_b32 s25, s7, s25
	s_cselect_b32 s65, s23, s62
	s_cselect_b32 s64, s22, s61
	v_lshl_add_u64 v[130:131], s[26:27], 0, v[72:73]
	s_add_i32 m0, s45, 0xc000
	ds_read_b128 v[98:101], v78
	ds_read_b128 v[102:105], v78 offset:1024
	ds_read_b128 v[106:109], v78 offset:2048
	ds_read_b128 v[110:113], v78 offset:3072
	ds_read_b128 v[114:117], v78 offset:4096
	ds_read_b128 v[118:121], v78 offset:5120
	ds_read_b128 v[122:125], v78 offset:6144
	ds_read_b128 v[126:129], v78 offset:7168
	global_load_lds_dwordx4 v[130:131], off
	v_lshl_add_u64 v[130:131], s[26:27], 0, v[74:75]
	s_add_i32 m0, s45, 0xe000
	s_nop 0
	global_load_lds_dwordx4 v[130:131], off
	s_waitcnt vmcnt(8)
	s_waitcnt lgkmcnt(0)
	s_barrier
	s_setprio 1
	s_waitcnt lgkmcnt(0)
	v_mfma_f32_16x16x32_bf16 v[60:63], v[80:83], v[98:101], v[60:63]
	v_mfma_f32_16x16x32_bf16 v[56:59], v[88:91], v[98:101], v[56:59]
	v_mfma_f32_16x16x32_bf16 v[52:55], v[80:83], v[106:109], v[52:55]
	v_mfma_f32_16x16x32_bf16 v[48:51], v[88:91], v[106:109], v[48:51]
	v_mfma_f32_16x16x32_bf16 v[44:47], v[80:83], v[114:117], v[44:47]
	v_mfma_f32_16x16x32_bf16 v[40:43], v[88:91], v[114:117], v[40:43]
	v_mfma_f32_16x16x32_bf16 v[36:39], v[80:83], v[122:125], v[36:39]
	v_mfma_f32_16x16x32_bf16 v[32:35], v[88:91], v[122:125], v[32:35]
	v_mfma_f32_16x16x32_bf16 v[60:63], v[84:87], v[102:105], v[60:63]
	v_mfma_f32_16x16x32_bf16 v[56:59], v[94:97], v[102:105], v[56:59]
	v_mfma_f32_16x16x32_bf16 v[52:55], v[84:87], v[110:113], v[52:55]
	v_mfma_f32_16x16x32_bf16 v[48:51], v[94:97], v[110:113], v[48:51]
	v_mfma_f32_16x16x32_bf16 v[44:47], v[84:87], v[118:121], v[44:47]
	v_mfma_f32_16x16x32_bf16 v[40:43], v[94:97], v[118:121], v[40:43]
	v_mfma_f32_16x16x32_bf16 v[36:39], v[84:87], v[126:129], v[36:39]
	v_mfma_f32_16x16x32_bf16 v[32:35], v[94:97], v[126:129], v[32:35]
	s_setprio 0
	s_setprio 1
	s_setprio 0
	s_barrier
	s_add_i32 s66, s66, s40
	v_lshl_add_u64 v[130:131], s[64:65], 0, v[92:93]
	s_mov_b32 m0, s66
	s_nop 0
	global_load_lds_dwordx4 v[130:131], off
	s_add_i32 m0, s66, 0x2000
	v_lshl_add_u64 v[132:133], s[64:65], 0, v[68:69]
	s_add_u32 s64, s64, s8
	s_addc_u32 s65, s65, s9
	global_load_lds_dwordx4 v[132:133], off
	v_lshl_add_u64 v[134:135], s[64:65], 0, v[92:93]
	s_mov_b32 m0, s46
	v_lshl_add_u64 v[136:137], s[64:65], 0, v[68:69]
	global_load_lds_dwordx4 v[134:135], off
	s_mov_b32 m0, s47
	v_lshl_add_u64 v[138:139], s[24:25], 0, v[64:65]
	global_load_lds_dwordx4 v[136:137], off
	s_mov_b32 m0, s45
	v_lshl_add_u64 v[140:141], s[24:25], 0, v[66:67]
	global_load_lds_dwordx4 v[138:139], off
	s_mov_b32 m0, s48
	s_nop 0
	global_load_lds_dwordx4 v[140:141], off
	ds_read_b128 v[98:101], v78 offset:16384
	ds_read_b128 v[102:105], v78 offset:17408
	ds_read_b128 v[106:109], v78 offset:18432
	ds_read_b128 v[110:113], v78 offset:19456
	ds_read_b128 v[114:117], v78 offset:20480
	ds_read_b128 v[118:121], v78 offset:21504
	ds_read_b128 v[122:125], v78 offset:22528
	ds_read_b128 v[126:129], v78 offset:23552
	s_waitcnt vmcnt(8)
	s_waitcnt lgkmcnt(0)
	s_barrier
	s_setprio 1
	s_waitcnt lgkmcnt(0)
	v_mfma_f32_16x16x32_bf16 v[28:31], v[80:83], v[98:101], v[28:31]
	v_mfma_f32_16x16x32_bf16 v[24:27], v[88:91], v[98:101], v[24:27]
	v_mfma_f32_16x16x32_bf16 v[20:23], v[80:83], v[106:109], v[20:23]
	v_mfma_f32_16x16x32_bf16 v[16:19], v[88:91], v[106:109], v[16:19]
	v_mfma_f32_16x16x32_bf16 v[12:15], v[80:83], v[114:117], v[12:15]
	v_mfma_f32_16x16x32_bf16 v[8:11], v[88:91], v[114:117], v[8:11]
	v_mfma_f32_16x16x32_bf16 v[4:7], v[80:83], v[122:125], v[4:7]
	v_mfma_f32_16x16x32_bf16 v[0:3], v[88:91], v[122:125], v[0:3]
	v_mfma_f32_16x16x32_bf16 v[28:31], v[84:87], v[102:105], v[28:31]
	v_mfma_f32_16x16x32_bf16 v[24:27], v[94:97], v[102:105], v[24:27]
	v_mfma_f32_16x16x32_bf16 v[20:23], v[84:87], v[110:113], v[20:23]
	v_mfma_f32_16x16x32_bf16 v[16:19], v[94:97], v[110:113], v[16:19]
	v_mfma_f32_16x16x32_bf16 v[12:15], v[84:87], v[118:121], v[12:15]
	v_mfma_f32_16x16x32_bf16 v[8:11], v[94:97], v[118:121], v[8:11]
	v_mfma_f32_16x16x32_bf16 v[4:7], v[84:87], v[126:129], v[4:7]
	v_mfma_f32_16x16x32_bf16 v[0:3], v[94:97], v[126:129], v[0:3]
	s_setprio 0
	s_setprio 1
	s_setprio 0
	s_barrier
	s_add_i32 s64, 0, 0x18000
	v_add_u32_e32 v79, s64, v77
	ds_read_b128 v[80:83], v79
	ds_read_b128 v[84:87], v79 offset:1024
	ds_read_b128 v[88:91], v79 offset:2048
	ds_read_b128 v[94:97], v79 offset:3072
	s_add_u32 s24, s24, s12
	s_addc_u32 s25, s25, s13
	s_mov_b32 m0, s49
	v_lshl_add_u64 v[142:143], s[24:25], 0, v[64:65]
	ds_read_b128 v[98:101], v78 offset:32768
	ds_read_b128 v[102:105], v78 offset:33792
	ds_read_b128 v[106:109], v78 offset:34816
	ds_read_b128 v[110:113], v78 offset:35840
	ds_read_b128 v[114:117], v78 offset:36864
	ds_read_b128 v[118:121], v78 offset:37888
	ds_read_b128 v[122:125], v78 offset:38912
	ds_read_b128 v[126:129], v78 offset:39936
	global_load_lds_dwordx4 v[142:143], off
	v_lshl_add_u64 v[142:143], s[24:25], 0, v[66:67]
	s_mov_b32 m0, s50
	s_nop 0
	global_load_lds_dwordx4 v[142:143], off
	s_waitcnt vmcnt(8)
	s_waitcnt lgkmcnt(0)
	s_barrier
	s_setprio 1
	s_waitcnt lgkmcnt(0)
	v_mfma_f32_16x16x32_bf16 v[60:63], v[80:83], v[98:101], v[60:63]
	v_mfma_f32_16x16x32_bf16 v[56:59], v[88:91], v[98:101], v[56:59]
	v_mfma_f32_16x16x32_bf16 v[52:55], v[80:83], v[106:109], v[52:55]
	v_mfma_f32_16x16x32_bf16 v[48:51], v[88:91], v[106:109], v[48:51]
	v_mfma_f32_16x16x32_bf16 v[44:47], v[80:83], v[114:117], v[44:47]
	v_mfma_f32_16x16x32_bf16 v[40:43], v[88:91], v[114:117], v[40:43]
	v_mfma_f32_16x16x32_bf16 v[36:39], v[80:83], v[122:125], v[36:39]
	v_mfma_f32_16x16x32_bf16 v[32:35], v[88:91], v[122:125], v[32:35]
	v_mfma_f32_16x16x32_bf16 v[60:63], v[84:87], v[102:105], v[60:63]
	v_mfma_f32_16x16x32_bf16 v[56:59], v[94:97], v[102:105], v[56:59]
	v_mfma_f32_16x16x32_bf16 v[52:55], v[84:87], v[110:113], v[52:55]
	v_mfma_f32_16x16x32_bf16 v[48:51], v[94:97], v[110:113], v[48:51]
	v_mfma_f32_16x16x32_bf16 v[44:47], v[84:87], v[118:121], v[44:47]
	v_mfma_f32_16x16x32_bf16 v[40:43], v[94:97], v[118:121], v[40:43]
	v_mfma_f32_16x16x32_bf16 v[36:39], v[84:87], v[126:129], v[36:39]
	v_mfma_f32_16x16x32_bf16 v[32:35], v[94:97], v[126:129], v[32:35]
	s_setprio 0
	s_setprio 1
	s_setprio 0
	s_barrier
	s_add_i32 s24, s64, s40
	v_lshl_add_u64 v[130:131], v[130:131], 0, s[80:81]
	s_mov_b32 m0, s24
	s_nop 0
	global_load_lds_dwordx4 v[130:131], off
	v_lshl_add_u64 v[130:131], v[132:133], 0, s[80:81]
	s_add_i32 m0, s24, 0x2000
	s_nop 0
	global_load_lds_dwordx4 v[130:131], off
	v_lshl_add_u64 v[130:131], v[134:135], 0, s[80:81]
	s_mov_b32 m0, s55
	s_nop 0
	global_load_lds_dwordx4 v[130:131], off
	v_lshl_add_u64 v[130:131], v[136:137], 0, s[80:81]
	s_mov_b32 m0, s56
	s_nop 0
	global_load_lds_dwordx4 v[130:131], off
	v_lshl_add_u64 v[130:131], v[138:139], 0, s[80:81]
	s_mov_b32 m0, s53
	s_nop 0
	global_load_lds_dwordx4 v[130:131], off
	v_lshl_add_u64 v[130:131], v[140:141], 0, s[80:81]
	s_mov_b32 m0, s54
	s_nop 0
	global_load_lds_dwordx4 v[130:131], off
	ds_read_b128 v[98:101], v78 offset:49152
	ds_read_b128 v[102:105], v78 offset:50176
	ds_read_b128 v[106:109], v78 offset:51200
	ds_read_b128 v[110:113], v78 offset:52224
	ds_read_b128 v[114:117], v78 offset:53248
	ds_read_b128 v[118:121], v78 offset:54272
	ds_read_b128 v[122:125], v78 offset:55296
	ds_read_b128 v[126:129], v78 offset:56320
	s_waitcnt vmcnt(8)
	s_waitcnt lgkmcnt(0)
	s_barrier
	s_setprio 1
	s_waitcnt lgkmcnt(0)
	v_mfma_f32_16x16x32_bf16 v[28:31], v[80:83], v[98:101], v[28:31]
	v_mfma_f32_16x16x32_bf16 v[24:27], v[88:91], v[98:101], v[24:27]
	v_mfma_f32_16x16x32_bf16 v[20:23], v[80:83], v[106:109], v[20:23]
	v_mfma_f32_16x16x32_bf16 v[16:19], v[88:91], v[106:109], v[16:19]
	v_mfma_f32_16x16x32_bf16 v[12:15], v[80:83], v[114:117], v[12:15]
	v_mfma_f32_16x16x32_bf16 v[8:11], v[88:91], v[114:117], v[8:11]
	v_mfma_f32_16x16x32_bf16 v[4:7], v[80:83], v[122:125], v[4:7]
	v_mfma_f32_16x16x32_bf16 v[0:3], v[88:91], v[122:125], v[0:3]
	v_mfma_f32_16x16x32_bf16 v[28:31], v[84:87], v[102:105], v[28:31]
	v_mfma_f32_16x16x32_bf16 v[24:27], v[94:97], v[102:105], v[24:27]
	v_mfma_f32_16x16x32_bf16 v[20:23], v[84:87], v[110:113], v[20:23]
	v_mfma_f32_16x16x32_bf16 v[16:19], v[94:97], v[110:113], v[16:19]
	v_mfma_f32_16x16x32_bf16 v[12:15], v[84:87], v[118:121], v[12:15]
	v_mfma_f32_16x16x32_bf16 v[8:11], v[94:97], v[118:121], v[8:11]
	v_mfma_f32_16x16x32_bf16 v[4:7], v[84:87], v[126:129], v[4:7]
	v_mfma_f32_16x16x32_bf16 v[0:3], v[94:97], v[126:129], v[0:3]
	s_setprio 0
	s_setprio 1
	s_setprio 0
	s_barrier
	s_add_u32 s26, s26, 0x100
	s_addc_u32 s27, s27, 0
	s_add_u32 s61, s61, 0x100
	s_addc_u32 s62, s62, 0
	s_cmp_ge_i32 s63, s51
	s_mov_b32 s24, s63
	s_cbranch_scc0 .LBB0_962

.LBB0_1518:
	s_add_i32 s63, s30, 2
	s_add_u32 s64, s28, 0x80
	s_addc_u32 s31, s29, 0
	s_add_i32 s66, 0, 0x10000
	s_cmp_eq_u32 s55, s30
	s_cselect_b32 s31, s7, s31
	s_cselect_b32 s30, s6, s64
	s_cselect_b32 s65, s27, s62
	s_cselect_b32 s64, s26, s61
	s_add_i32 s67, 0, 0x14000
	v_add_u32_e32 v142, s66, v164
	v_add_u32_e32 v156, s67, v164
	v_lshl_add_u64 v[252:253], s[28:29], 0, v[152:153]
	s_add_i32 m0, s46, 0xc000
	s_nop 0
	global_load_lds_dwordx4 v[252:253], off
	v_lshl_add_u64 v[252:253], s[28:29], 0, v[154:155]
	s_add_i32 m0, s46, 0xe000
	s_nop 0
	global_load_lds_dwordx4 v[252:253], off
	ds_read_b128 v[130:133], v142
	ds_read_b128 v[134:137], v142 offset:1024
	ds_read_b128 v[138:141], v142 offset:2048
	ds_read_b128 v[142:145], v142 offset:3072
	ds_read_b128 v[160:163], v156
	ds_read_b128 v[168:171], v156 offset:1024
	ds_read_b128 v[172:175], v156 offset:2048
	ds_read_b128 v[176:179], v156 offset:3072
	ds_read_b128 v[180:183], v166
	ds_read_b128 v[184:187], v166 offset:1024
	ds_read_b128 v[188:191], v166 offset:2048
	ds_read_b128 v[192:195], v166 offset:3072
	ds_read_b128 v[214:217], v166 offset:4096
	ds_read_b128 v[218:221], v166 offset:5120
	ds_read_b128 v[222:225], v166 offset:6144
	ds_read_b128 v[226:229], v166 offset:7168
	s_waitcnt vmcnt(8)
	s_waitcnt lgkmcnt(0)
	s_barrier
	s_setprio 1
	s_waitcnt lgkmcnt(0)
	v_mfma_f32_16x16x32_bf16 v[126:129], v[130:133], v[180:183], v[126:129]
	v_mfma_f32_16x16x32_bf16 v[122:125], v[138:141], v[180:183], v[122:125]
	v_mfma_f32_16x16x32_bf16 v[110:113], v[130:133], v[188:191], v[110:113]
	v_mfma_f32_16x16x32_bf16 v[106:109], v[138:141], v[188:191], v[106:109]
	v_mfma_f32_16x16x32_bf16 v[94:97], v[130:133], v[214:217], v[94:97]
	v_mfma_f32_16x16x32_bf16 v[88:91], v[138:141], v[214:217], v[88:91]
	v_mfma_f32_16x16x32_bf16 v[76:79], v[130:133], v[222:225], v[76:79]
	v_mfma_f32_16x16x32_bf16 v[72:75], v[138:141], v[222:225], v[72:75]
	v_mfma_f32_16x16x32_bf16 v[126:129], v[134:137], v[184:187], v[126:129]
	v_mfma_f32_16x16x32_bf16 v[122:125], v[142:145], v[184:187], v[122:125]
	v_mfma_f32_16x16x32_bf16 v[110:113], v[134:137], v[192:195], v[110:113]
	v_mfma_f32_16x16x32_bf16 v[106:109], v[142:145], v[192:195], v[106:109]
	v_mfma_f32_16x16x32_bf16 v[94:97], v[134:137], v[218:221], v[94:97]
	v_mfma_f32_16x16x32_bf16 v[88:91], v[142:145], v[218:221], v[88:91]
	v_mfma_f32_16x16x32_bf16 v[76:79], v[134:137], v[226:229], v[76:79]
	v_mfma_f32_16x16x32_bf16 v[72:75], v[142:145], v[226:229], v[72:75]
	s_setprio 0
	s_setprio 1
	v_mfma_f32_16x16x32_bf16 v[118:121], v[160:163], v[180:183], v[118:121]
	v_mfma_f32_16x16x32_bf16 v[114:117], v[172:175], v[180:183], v[114:117]
	v_mfma_f32_16x16x32_bf16 v[102:105], v[160:163], v[188:191], v[102:105]
	v_mfma_f32_16x16x32_bf16 v[98:101], v[172:175], v[188:191], v[98:101]
	v_mfma_f32_16x16x32_bf16 v[84:87], v[160:163], v[214:217], v[84:87]
	v_mfma_f32_16x16x32_bf16 v[80:83], v[172:175], v[214:217], v[80:83]
	v_mfma_f32_16x16x32_bf16 v[68:71], v[160:163], v[222:225], v[68:71]
	v_mfma_f32_16x16x32_bf16 v[64:67], v[172:175], v[222:225], v[64:67]
	v_mfma_f32_16x16x32_bf16 v[118:121], v[168:171], v[184:187], v[118:121]
	v_mfma_f32_16x16x32_bf16 v[114:117], v[176:179], v[184:187], v[114:117]
	v_mfma_f32_16x16x32_bf16 v[102:105], v[168:171], v[192:195], v[102:105]
	v_mfma_f32_16x16x32_bf16 v[98:101], v[176:179], v[192:195], v[98:101]
	v_mfma_f32_16x16x32_bf16 v[84:87], v[168:171], v[218:221], v[84:87]
	v_mfma_f32_16x16x32_bf16 v[80:83], v[176:179], v[218:221], v[80:83]
	v_mfma_f32_16x16x32_bf16 v[68:71], v[168:171], v[226:229], v[68:71]
	v_mfma_f32_16x16x32_bf16 v[64:67], v[176:179], v[226:229], v[64:67]
	s_setprio 0
	s_barrier
	s_add_i32 s66, s66, s41
	v_lshl_add_u64 v[156:157], s[64:65], 0, v[92:93]
	s_mov_b32 m0, s66
	s_nop 0
	global_load_lds_dwordx4 v[156:157], off
	s_add_i32 m0, s66, 0x2000
	v_lshl_add_u64 v[230:231], s[64:65], 0, v[150:151]
	s_add_u32 s64, s64, s8
	s_addc_u32 s65, s65, s9
	s_add_i32 s66, s67, s41
	global_load_lds_dwordx4 v[230:231], off
	v_lshl_add_u64 v[232:233], s[64:65], 0, v[92:93]
	s_mov_b32 m0, s66
	v_lshl_add_u64 v[234:235], s[64:65], 0, v[150:151]
	global_load_lds_dwordx4 v[232:233], off
	s_add_i32 m0, s66, 0x2000
	v_lshl_add_u64 v[236:237], s[30:31], 0, v[146:147]
	global_load_lds_dwordx4 v[234:235], off
	s_mov_b32 m0, s46
	v_lshl_add_u64 v[238:239], s[30:31], 0, v[148:149]
	global_load_lds_dwordx4 v[236:237], off
	s_mov_b32 m0, s47
	s_nop 0
	global_load_lds_dwordx4 v[238:239], off
	ds_read_b128 v[180:183], v166 offset:16384
	ds_read_b128 v[184:187], v166 offset:17408
	ds_read_b128 v[188:191], v166 offset:18432
	ds_read_b128 v[192:195], v166 offset:19456
	ds_read_b128 v[214:217], v166 offset:20480
	ds_read_b128 v[218:221], v166 offset:21504
	ds_read_b128 v[222:225], v166 offset:22528
	ds_read_b128 v[226:229], v166 offset:23552
	s_waitcnt vmcnt(8)
	s_waitcnt lgkmcnt(0)
	s_barrier
	s_setprio 1
	s_waitcnt lgkmcnt(0)
	v_mfma_f32_16x16x32_bf16 v[60:63], v[130:133], v[180:183], v[60:63]
	v_mfma_f32_16x16x32_bf16 v[56:59], v[138:141], v[180:183], v[56:59]
	v_mfma_f32_16x16x32_bf16 v[44:47], v[130:133], v[188:191], v[44:47]
	v_mfma_f32_16x16x32_bf16 v[40:43], v[138:141], v[188:191], v[40:43]
	v_mfma_f32_16x16x32_bf16 v[28:31], v[130:133], v[214:217], v[28:31]
	v_mfma_f32_16x16x32_bf16 v[24:27], v[138:141], v[214:217], v[24:27]
	v_mfma_f32_16x16x32_bf16 v[12:15], v[130:133], v[222:225], v[12:15]
	v_mfma_f32_16x16x32_bf16 v[8:11], v[138:141], v[222:225], v[8:11]
	v_mfma_f32_16x16x32_bf16 v[60:63], v[134:137], v[184:187], v[60:63]
	v_mfma_f32_16x16x32_bf16 v[56:59], v[142:145], v[184:187], v[56:59]
	v_mfma_f32_16x16x32_bf16 v[44:47], v[134:137], v[192:195], v[44:47]
	v_mfma_f32_16x16x32_bf16 v[40:43], v[142:145], v[192:195], v[40:43]
	v_mfma_f32_16x16x32_bf16 v[28:31], v[134:137], v[218:221], v[28:31]
	v_mfma_f32_16x16x32_bf16 v[24:27], v[142:145], v[218:221], v[24:27]
	v_mfma_f32_16x16x32_bf16 v[12:15], v[134:137], v[226:229], v[12:15]
	v_mfma_f32_16x16x32_bf16 v[8:11], v[142:145], v[226:229], v[8:11]
	s_setprio 0
	s_setprio 1
	v_mfma_f32_16x16x32_bf16 v[52:55], v[160:163], v[180:183], v[52:55]
	v_mfma_f32_16x16x32_bf16 v[48:51], v[172:175], v[180:183], v[48:51]
	v_mfma_f32_16x16x32_bf16 v[36:39], v[160:163], v[188:191], v[36:39]
	v_mfma_f32_16x16x32_bf16 v[32:35], v[172:175], v[188:191], v[32:35]
	v_mfma_f32_16x16x32_bf16 v[20:23], v[160:163], v[214:217], v[20:23]
	v_mfma_f32_16x16x32_bf16 v[16:19], v[172:175], v[214:217], v[16:19]
	v_mfma_f32_16x16x32_bf16 v[4:7], v[160:163], v[222:225], v[4:7]
	v_mfma_f32_16x16x32_bf16 v[0:3], v[172:175], v[222:225], v[0:3]
	v_mfma_f32_16x16x32_bf16 v[52:55], v[168:171], v[184:187], v[52:55]
	v_mfma_f32_16x16x32_bf16 v[48:51], v[176:179], v[184:187], v[48:51]
	v_mfma_f32_16x16x32_bf16 v[36:39], v[168:171], v[192:195], v[36:39]
	v_mfma_f32_16x16x32_bf16 v[32:35], v[176:179], v[192:195], v[32:35]
	v_mfma_f32_16x16x32_bf16 v[20:23], v[168:171], v[218:221], v[20:23]
	v_mfma_f32_16x16x32_bf16 v[16:19], v[176:179], v[218:221], v[16:19]
	v_mfma_f32_16x16x32_bf16 v[4:7], v[168:171], v[226:229], v[4:7]
	v_mfma_f32_16x16x32_bf16 v[0:3], v[176:179], v[226:229], v[0:3]
	s_setprio 0
	s_barrier
	s_add_i32 s64, 0, 0x18000
	s_add_i32 s65, 0, 0x1c000
	v_add_u32_e32 v142, s64, v164
	v_add_u32_e32 v167, s65, v164
	s_add_u32 s30, s30, s12
	s_addc_u32 s31, s31, s13
	s_mov_b32 m0, s48
	v_lshl_add_u64 v[240:241], s[30:31], 0, v[146:147]
	global_load_lds_dwordx4 v[240:241], off
	v_lshl_add_u64 v[240:241], s[30:31], 0, v[148:149]
	s_mov_b32 m0, s49
	s_nop 0
	global_load_lds_dwordx4 v[240:241], off
	ds_read_b128 v[130:133], v142
	ds_read_b128 v[134:137], v142 offset:1024
	ds_read_b128 v[138:141], v142 offset:2048
	ds_read_b128 v[142:145], v142 offset:3072
	ds_read_b128 v[160:163], v167
	ds_read_b128 v[168:171], v167 offset:1024
	ds_read_b128 v[172:175], v167 offset:2048
	ds_read_b128 v[176:179], v167 offset:3072
	ds_read_b128 v[180:183], v166 offset:32768
	ds_read_b128 v[184:187], v166 offset:33792
	ds_read_b128 v[188:191], v166 offset:34816
	ds_read_b128 v[192:195], v166 offset:35840
	ds_read_b128 v[214:217], v166 offset:36864
	ds_read_b128 v[218:221], v166 offset:37888
	ds_read_b128 v[222:225], v166 offset:38912
	ds_read_b128 v[226:229], v166 offset:39936
	s_waitcnt vmcnt(8)
	s_waitcnt lgkmcnt(0)
	s_barrier
	s_setprio 1
	s_waitcnt lgkmcnt(0)
	v_mfma_f32_16x16x32_bf16 v[126:129], v[130:133], v[180:183], v[126:129]
	v_mfma_f32_16x16x32_bf16 v[122:125], v[138:141], v[180:183], v[122:125]
	v_mfma_f32_16x16x32_bf16 v[110:113], v[130:133], v[188:191], v[110:113]
	v_mfma_f32_16x16x32_bf16 v[106:109], v[138:141], v[188:191], v[106:109]
	v_mfma_f32_16x16x32_bf16 v[94:97], v[130:133], v[214:217], v[94:97]
	v_mfma_f32_16x16x32_bf16 v[88:91], v[138:141], v[214:217], v[88:91]
	v_mfma_f32_16x16x32_bf16 v[76:79], v[130:133], v[222:225], v[76:79]
	v_mfma_f32_16x16x32_bf16 v[72:75], v[138:141], v[222:225], v[72:75]
	v_mfma_f32_16x16x32_bf16 v[126:129], v[134:137], v[184:187], v[126:129]
	v_mfma_f32_16x16x32_bf16 v[122:125], v[142:145], v[184:187], v[122:125]
	v_mfma_f32_16x16x32_bf16 v[110:113], v[134:137], v[192:195], v[110:113]
	v_mfma_f32_16x16x32_bf16 v[106:109], v[142:145], v[192:195], v[106:109]
	v_mfma_f32_16x16x32_bf16 v[94:97], v[134:137], v[218:221], v[94:97]
	v_mfma_f32_16x16x32_bf16 v[88:91], v[142:145], v[218:221], v[88:91]
	v_mfma_f32_16x16x32_bf16 v[76:79], v[134:137], v[226:229], v[76:79]
	v_mfma_f32_16x16x32_bf16 v[72:75], v[142:145], v[226:229], v[72:75]
	s_setprio 0
	s_setprio 1
	v_mfma_f32_16x16x32_bf16 v[118:121], v[160:163], v[180:183], v[118:121]
	v_mfma_f32_16x16x32_bf16 v[114:117], v[172:175], v[180:183], v[114:117]
	v_mfma_f32_16x16x32_bf16 v[102:105], v[160:163], v[188:191], v[102:105]
	v_mfma_f32_16x16x32_bf16 v[98:101], v[172:175], v[188:191], v[98:101]
	v_mfma_f32_16x16x32_bf16 v[84:87], v[160:163], v[214:217], v[84:87]
	v_mfma_f32_16x16x32_bf16 v[80:83], v[172:175], v[214:217], v[80:83]
	v_mfma_f32_16x16x32_bf16 v[68:71], v[160:163], v[222:225], v[68:71]
	v_mfma_f32_16x16x32_bf16 v[64:67], v[172:175], v[222:225], v[64:67]
	v_mfma_f32_16x16x32_bf16 v[118:121], v[168:171], v[184:187], v[118:121]
	v_mfma_f32_16x16x32_bf16 v[114:117], v[176:179], v[184:187], v[114:117]
	v_mfma_f32_16x16x32_bf16 v[102:105], v[168:171], v[192:195], v[102:105]
	v_mfma_f32_16x16x32_bf16 v[98:101], v[176:179], v[192:195], v[98:101]
	v_mfma_f32_16x16x32_bf16 v[84:87], v[168:171], v[218:221], v[84:87]
	v_mfma_f32_16x16x32_bf16 v[80:83], v[176:179], v[218:221], v[80:83]
	v_mfma_f32_16x16x32_bf16 v[68:71], v[168:171], v[226:229], v[68:71]
	v_mfma_f32_16x16x32_bf16 v[64:67], v[176:179], v[226:229], v[64:67]
	s_setprio 0
	s_barrier
	s_add_i32 s30, s64, s41
	v_lshl_add_u64 v[156:157], v[156:157], 0, s[80:81]
	s_mov_b32 m0, s30
	s_nop 0
	global_load_lds_dwordx4 v[156:157], off
	v_lshl_add_u64 v[156:157], v[230:231], 0, s[80:81]
	s_add_i32 m0, s30, 0x2000
	s_add_i32 s30, s65, s41
	global_load_lds_dwordx4 v[156:157], off
	v_lshl_add_u64 v[156:157], v[232:233], 0, s[80:81]
	s_mov_b32 m0, s30
	s_nop 0
	global_load_lds_dwordx4 v[156:157], off
	v_lshl_add_u64 v[156:157], v[234:235], 0, s[80:81]
	s_add_i32 m0, s30, 0x2000
	s_nop 0
	global_load_lds_dwordx4 v[156:157], off
	v_lshl_add_u64 v[156:157], v[236:237], 0, s[80:81]
	s_mov_b32 m0, s53
	s_nop 0
	global_load_lds_dwordx4 v[156:157], off
	v_lshl_add_u64 v[156:157], v[238:239], 0, s[80:81]
	s_mov_b32 m0, s54
	s_nop 0
	global_load_lds_dwordx4 v[156:157], off
	ds_read_b128 v[180:183], v166 offset:49152
	ds_read_b128 v[184:187], v166 offset:50176
	ds_read_b128 v[188:191], v166 offset:51200
	ds_read_b128 v[192:195], v166 offset:52224
	ds_read_b128 v[214:217], v166 offset:53248
	ds_read_b128 v[218:221], v166 offset:54272
	ds_read_b128 v[222:225], v166 offset:55296
	ds_read_b128 v[226:229], v166 offset:56320
	s_waitcnt vmcnt(8)
	s_waitcnt lgkmcnt(0)
	s_barrier
	s_setprio 1
	s_waitcnt lgkmcnt(0)
	v_mfma_f32_16x16x32_bf16 v[60:63], v[130:133], v[180:183], v[60:63]
	v_mfma_f32_16x16x32_bf16 v[56:59], v[138:141], v[180:183], v[56:59]
	v_mfma_f32_16x16x32_bf16 v[44:47], v[130:133], v[188:191], v[44:47]
	v_mfma_f32_16x16x32_bf16 v[40:43], v[138:141], v[188:191], v[40:43]
	v_mfma_f32_16x16x32_bf16 v[28:31], v[130:133], v[214:217], v[28:31]
	v_mfma_f32_16x16x32_bf16 v[24:27], v[138:141], v[214:217], v[24:27]
	v_mfma_f32_16x16x32_bf16 v[12:15], v[130:133], v[222:225], v[12:15]
	v_mfma_f32_16x16x32_bf16 v[8:11], v[138:141], v[222:225], v[8:11]
	v_mfma_f32_16x16x32_bf16 v[60:63], v[134:137], v[184:187], v[60:63]
	v_mfma_f32_16x16x32_bf16 v[56:59], v[142:145], v[184:187], v[56:59]
	v_mfma_f32_16x16x32_bf16 v[44:47], v[134:137], v[192:195], v[44:47]
	v_mfma_f32_16x16x32_bf16 v[40:43], v[142:145], v[192:195], v[40:43]
	v_mfma_f32_16x16x32_bf16 v[28:31], v[134:137], v[218:221], v[28:31]
	v_mfma_f32_16x16x32_bf16 v[24:27], v[142:145], v[218:221], v[24:27]
	v_mfma_f32_16x16x32_bf16 v[12:15], v[134:137], v[226:229], v[12:15]
	v_mfma_f32_16x16x32_bf16 v[8:11], v[142:145], v[226:229], v[8:11]
	s_setprio 0
	s_setprio 1
	v_mfma_f32_16x16x32_bf16 v[52:55], v[160:163], v[180:183], v[52:55]
	v_mfma_f32_16x16x32_bf16 v[48:51], v[172:175], v[180:183], v[48:51]
	v_mfma_f32_16x16x32_bf16 v[36:39], v[160:163], v[188:191], v[36:39]
	v_mfma_f32_16x16x32_bf16 v[32:35], v[172:175], v[188:191], v[32:35]
	v_mfma_f32_16x16x32_bf16 v[20:23], v[160:163], v[214:217], v[20:23]
	v_mfma_f32_16x16x32_bf16 v[16:19], v[172:175], v[214:217], v[16:19]
	v_mfma_f32_16x16x32_bf16 v[4:7], v[160:163], v[222:225], v[4:7]
	v_mfma_f32_16x16x32_bf16 v[0:3], v[172:175], v[222:225], v[0:3]
	v_mfma_f32_16x16x32_bf16 v[52:55], v[168:171], v[184:187], v[52:55]
	v_mfma_f32_16x16x32_bf16 v[48:51], v[176:179], v[184:187], v[48:51]
	v_mfma_f32_16x16x32_bf16 v[36:39], v[168:171], v[192:195], v[36:39]
	v_mfma_f32_16x16x32_bf16 v[32:35], v[176:179], v[192:195], v[32:35]
	v_mfma_f32_16x16x32_bf16 v[20:23], v[168:171], v[218:221], v[20:23]
	v_mfma_f32_16x16x32_bf16 v[16:19], v[176:179], v[218:221], v[16:19]
	v_mfma_f32_16x16x32_bf16 v[4:7], v[168:171], v[226:229], v[4:7]
	v_mfma_f32_16x16x32_bf16 v[0:3], v[176:179], v[226:229], v[0:3]
	s_setprio 0
	s_barrier
	s_add_u32 s28, s28, 0x100
	s_addc_u32 s29, s29, 0
	s_add_u32 s61, s61, 0x100
	s_addc_u32 s62, s62, 0
	s_cmp_ge_i32 s63, s52
	s_mov_b32 s30, s63
	s_cbranch_scc0 .LBB0_1518
	s_movk_i32 s67, 0x4000

.LBB0_1603:
	s_add_i32 s59, s28, 2
	s_add_u32 s60, s26, 0x80
	s_addc_u32 s29, s27, 0
	s_add_i32 s62, 0, 0x10000
	s_cmp_eq_u32 s53, s28
	s_cselect_b32 s29, s7, s29
	s_cselect_b32 s28, s6, s60
	v_add_u32_e32 v156, s62, v141
	s_cselect_b32 s61, s25, s58
	s_cselect_b32 s60, s24, s57
	s_add_i32 s63, 0, 0x14000
	v_lshl_add_u64 v[252:253], s[26:27], 0, v[136:137]
	s_add_i32 m0, s44, 0xc000
	s_nop 0
	global_load_lds_dwordx4 v[252:253], off
	v_lshl_add_u64 v[252:253], s[26:27], 0, v[138:139]
	s_add_i32 m0, s44, 0xe000
	s_nop 0
	global_load_lds_dwordx4 v[252:253], off
	ds_read_b128 v[144:147], v156
	ds_read_b128 v[148:151], v156 offset:1024
	ds_read_b128 v[152:155], v156 offset:2048
	ds_read_b128 v[160:163], v156 offset:3072
	v_add_u32_e32 v156, s63, v141
	ds_read_b128 v[164:167], v156
	ds_read_b128 v[168:171], v156 offset:1024
	ds_read_b128 v[172:175], v156 offset:2048
	ds_read_b128 v[176:179], v156 offset:3072
	ds_read_b128 v[180:183], v143
	ds_read_b128 v[184:187], v143 offset:1024
	ds_read_b128 v[188:191], v143 offset:2048
	ds_read_b128 v[192:195], v143 offset:3072
	ds_read_b128 v[214:217], v143 offset:4096
	ds_read_b128 v[218:221], v143 offset:5120
	ds_read_b128 v[222:225], v143 offset:6144
	ds_read_b128 v[226:229], v143 offset:7168
	s_waitcnt vmcnt(8)
	s_waitcnt lgkmcnt(0)
	s_barrier
	s_setprio 1
	s_waitcnt lgkmcnt(0)
	v_mfma_f32_16x16x32_bf16 v[122:125], v[144:147], v[180:183], v[122:125]
	v_mfma_f32_16x16x32_bf16 v[126:129], v[152:155], v[180:183], v[126:129]
	v_mfma_f32_16x16x32_bf16 v[110:113], v[144:147], v[188:191], v[110:113]
	v_mfma_f32_16x16x32_bf16 v[106:109], v[152:155], v[188:191], v[106:109]
	v_mfma_f32_16x16x32_bf16 v[94:97], v[144:147], v[214:217], v[94:97]
	v_mfma_f32_16x16x32_bf16 v[88:91], v[152:155], v[214:217], v[88:91]
	v_mfma_f32_16x16x32_bf16 v[76:79], v[144:147], v[222:225], v[76:79]
	v_mfma_f32_16x16x32_bf16 v[72:75], v[152:155], v[222:225], v[72:75]
	v_mfma_f32_16x16x32_bf16 v[122:125], v[148:151], v[184:187], v[122:125]
	v_mfma_f32_16x16x32_bf16 v[126:129], v[160:163], v[184:187], v[126:129]
	v_mfma_f32_16x16x32_bf16 v[110:113], v[148:151], v[192:195], v[110:113]
	v_mfma_f32_16x16x32_bf16 v[106:109], v[160:163], v[192:195], v[106:109]
	v_mfma_f32_16x16x32_bf16 v[94:97], v[148:151], v[218:221], v[94:97]
	v_mfma_f32_16x16x32_bf16 v[88:91], v[160:163], v[218:221], v[88:91]
	v_mfma_f32_16x16x32_bf16 v[76:79], v[148:151], v[226:229], v[76:79]
	v_mfma_f32_16x16x32_bf16 v[72:75], v[160:163], v[226:229], v[72:75]
	s_setprio 0
	s_setprio 1
	v_mfma_f32_16x16x32_bf16 v[118:121], v[164:167], v[180:183], v[118:121]
	v_mfma_f32_16x16x32_bf16 v[114:117], v[172:175], v[180:183], v[114:117]
	v_mfma_f32_16x16x32_bf16 v[102:105], v[164:167], v[188:191], v[102:105]
	v_mfma_f32_16x16x32_bf16 v[98:101], v[172:175], v[188:191], v[98:101]
	v_mfma_f32_16x16x32_bf16 v[84:87], v[164:167], v[214:217], v[84:87]
	v_mfma_f32_16x16x32_bf16 v[80:83], v[172:175], v[214:217], v[80:83]
	v_mfma_f32_16x16x32_bf16 v[68:71], v[164:167], v[222:225], v[68:71]
	v_mfma_f32_16x16x32_bf16 v[64:67], v[172:175], v[222:225], v[64:67]
	v_mfma_f32_16x16x32_bf16 v[118:121], v[168:171], v[184:187], v[118:121]
	v_mfma_f32_16x16x32_bf16 v[114:117], v[176:179], v[184:187], v[114:117]
	v_mfma_f32_16x16x32_bf16 v[102:105], v[168:171], v[192:195], v[102:105]
	v_mfma_f32_16x16x32_bf16 v[98:101], v[176:179], v[192:195], v[98:101]
	v_mfma_f32_16x16x32_bf16 v[84:87], v[168:171], v[218:221], v[84:87]
	v_mfma_f32_16x16x32_bf16 v[80:83], v[176:179], v[218:221], v[80:83]
	v_mfma_f32_16x16x32_bf16 v[68:71], v[168:171], v[226:229], v[68:71]
	v_mfma_f32_16x16x32_bf16 v[64:67], v[176:179], v[226:229], v[64:67]
	s_setprio 0
	s_barrier
	s_add_i32 s62, s62, s39
	v_lshl_add_u64 v[156:157], s[60:61], 0, v[92:93]
	s_mov_b32 m0, s62
	s_nop 0
	global_load_lds_dwordx4 v[156:157], off
	s_add_i32 m0, s62, 0x2000
	v_lshl_add_u64 v[230:231], s[60:61], 0, v[134:135]
	s_add_u32 s60, s60, s8
	s_addc_u32 s61, s61, s9
	s_add_i32 s62, s63, s39
	global_load_lds_dwordx4 v[230:231], off
	v_lshl_add_u64 v[232:233], s[60:61], 0, v[92:93]
	s_mov_b32 m0, s62
	v_lshl_add_u64 v[234:235], s[60:61], 0, v[134:135]
	global_load_lds_dwordx4 v[232:233], off
	s_add_i32 m0, s62, 0x2000
	v_lshl_add_u64 v[236:237], s[28:29], 0, v[130:131]
	global_load_lds_dwordx4 v[234:235], off
	s_mov_b32 m0, s44
	v_lshl_add_u64 v[238:239], s[28:29], 0, v[132:133]
	global_load_lds_dwordx4 v[236:237], off
	s_mov_b32 m0, s45
	s_nop 0
	global_load_lds_dwordx4 v[238:239], off
	ds_read_b128 v[180:183], v143 offset:16384
	ds_read_b128 v[184:187], v143 offset:17408
	ds_read_b128 v[188:191], v143 offset:18432
	ds_read_b128 v[192:195], v143 offset:19456
	ds_read_b128 v[214:217], v143 offset:20480
	ds_read_b128 v[218:221], v143 offset:21504
	ds_read_b128 v[222:225], v143 offset:22528
	ds_read_b128 v[226:229], v143 offset:23552
	s_waitcnt vmcnt(8)
	s_waitcnt lgkmcnt(0)
	s_barrier
	s_setprio 1
	s_waitcnt lgkmcnt(0)
	v_mfma_f32_16x16x32_bf16 v[60:63], v[144:147], v[180:183], v[60:63]
	v_mfma_f32_16x16x32_bf16 v[56:59], v[152:155], v[180:183], v[56:59]
	v_mfma_f32_16x16x32_bf16 v[44:47], v[144:147], v[188:191], v[44:47]
	v_mfma_f32_16x16x32_bf16 v[40:43], v[152:155], v[188:191], v[40:43]
	v_mfma_f32_16x16x32_bf16 v[28:31], v[144:147], v[214:217], v[28:31]
	v_mfma_f32_16x16x32_bf16 v[24:27], v[152:155], v[214:217], v[24:27]
	v_mfma_f32_16x16x32_bf16 v[12:15], v[144:147], v[222:225], v[12:15]
	v_mfma_f32_16x16x32_bf16 v[8:11], v[152:155], v[222:225], v[8:11]
	v_mfma_f32_16x16x32_bf16 v[60:63], v[148:151], v[184:187], v[60:63]
	v_mfma_f32_16x16x32_bf16 v[56:59], v[160:163], v[184:187], v[56:59]
	v_mfma_f32_16x16x32_bf16 v[44:47], v[148:151], v[192:195], v[44:47]
	v_mfma_f32_16x16x32_bf16 v[40:43], v[160:163], v[192:195], v[40:43]
	v_mfma_f32_16x16x32_bf16 v[28:31], v[148:151], v[218:221], v[28:31]
	v_mfma_f32_16x16x32_bf16 v[24:27], v[160:163], v[218:221], v[24:27]
	v_mfma_f32_16x16x32_bf16 v[12:15], v[148:151], v[226:229], v[12:15]
	v_mfma_f32_16x16x32_bf16 v[8:11], v[160:163], v[226:229], v[8:11]
	s_setprio 0
	s_setprio 1
	v_mfma_f32_16x16x32_bf16 v[52:55], v[164:167], v[180:183], v[52:55]
	v_mfma_f32_16x16x32_bf16 v[48:51], v[172:175], v[180:183], v[48:51]
	v_mfma_f32_16x16x32_bf16 v[36:39], v[164:167], v[188:191], v[36:39]
	v_mfma_f32_16x16x32_bf16 v[32:35], v[172:175], v[188:191], v[32:35]
	v_mfma_f32_16x16x32_bf16 v[20:23], v[164:167], v[214:217], v[20:23]
	v_mfma_f32_16x16x32_bf16 v[16:19], v[172:175], v[214:217], v[16:19]
	v_mfma_f32_16x16x32_bf16 v[4:7], v[164:167], v[222:225], v[4:7]
	v_mfma_f32_16x16x32_bf16 v[0:3], v[172:175], v[222:225], v[0:3]
	v_mfma_f32_16x16x32_bf16 v[52:55], v[168:171], v[184:187], v[52:55]
	v_mfma_f32_16x16x32_bf16 v[48:51], v[176:179], v[184:187], v[48:51]
	v_mfma_f32_16x16x32_bf16 v[36:39], v[168:171], v[192:195], v[36:39]
	v_mfma_f32_16x16x32_bf16 v[32:35], v[176:179], v[192:195], v[32:35]
	v_mfma_f32_16x16x32_bf16 v[20:23], v[168:171], v[218:221], v[20:23]
	v_mfma_f32_16x16x32_bf16 v[16:19], v[176:179], v[218:221], v[16:19]
	v_mfma_f32_16x16x32_bf16 v[4:7], v[168:171], v[226:229], v[4:7]
	v_mfma_f32_16x16x32_bf16 v[0:3], v[176:179], v[226:229], v[0:3]
	s_setprio 0
	s_barrier
	s_add_i32 s60, 0, 0x18000
	v_add_u32_e32 v159, s60, v141
	s_add_i32 s61, 0, 0x1c000
	s_add_u32 s28, s28, s12
	s_addc_u32 s29, s29, s13
	s_mov_b32 m0, s46
	v_lshl_add_u64 v[240:241], s[28:29], 0, v[130:131]
	global_load_lds_dwordx4 v[240:241], off
	v_lshl_add_u64 v[240:241], s[28:29], 0, v[132:133]
	s_mov_b32 m0, s47
	s_nop 0
	global_load_lds_dwordx4 v[240:241], off
	ds_read_b128 v[144:147], v159
	ds_read_b128 v[148:151], v159 offset:1024
	ds_read_b128 v[152:155], v159 offset:2048
	ds_read_b128 v[160:163], v159 offset:3072
	v_add_u32_e32 v159, s61, v141
	ds_read_b128 v[164:167], v159
	ds_read_b128 v[168:171], v159 offset:1024
	ds_read_b128 v[172:175], v159 offset:2048
	ds_read_b128 v[176:179], v159 offset:3072
	ds_read_b128 v[180:183], v143 offset:32768
	ds_read_b128 v[184:187], v143 offset:33792
	ds_read_b128 v[188:191], v143 offset:34816
	ds_read_b128 v[192:195], v143 offset:35840
	ds_read_b128 v[214:217], v143 offset:36864
	ds_read_b128 v[218:221], v143 offset:37888
	ds_read_b128 v[222:225], v143 offset:38912
	ds_read_b128 v[226:229], v143 offset:39936
	s_waitcnt vmcnt(8)
	s_waitcnt lgkmcnt(0)
	s_barrier
	s_setprio 1
	s_waitcnt lgkmcnt(0)
	v_mfma_f32_16x16x32_bf16 v[122:125], v[144:147], v[180:183], v[122:125]
	v_mfma_f32_16x16x32_bf16 v[126:129], v[152:155], v[180:183], v[126:129]
	v_mfma_f32_16x16x32_bf16 v[110:113], v[144:147], v[188:191], v[110:113]
	v_mfma_f32_16x16x32_bf16 v[106:109], v[152:155], v[188:191], v[106:109]
	v_mfma_f32_16x16x32_bf16 v[94:97], v[144:147], v[214:217], v[94:97]
	v_mfma_f32_16x16x32_bf16 v[88:91], v[152:155], v[214:217], v[88:91]
	v_mfma_f32_16x16x32_bf16 v[76:79], v[144:147], v[222:225], v[76:79]
	v_mfma_f32_16x16x32_bf16 v[72:75], v[152:155], v[222:225], v[72:75]
	v_mfma_f32_16x16x32_bf16 v[122:125], v[148:151], v[184:187], v[122:125]
	v_mfma_f32_16x16x32_bf16 v[126:129], v[160:163], v[184:187], v[126:129]
	v_mfma_f32_16x16x32_bf16 v[110:113], v[148:151], v[192:195], v[110:113]
	v_mfma_f32_16x16x32_bf16 v[106:109], v[160:163], v[192:195], v[106:109]
	v_mfma_f32_16x16x32_bf16 v[94:97], v[148:151], v[218:221], v[94:97]
	v_mfma_f32_16x16x32_bf16 v[88:91], v[160:163], v[218:221], v[88:91]
	v_mfma_f32_16x16x32_bf16 v[76:79], v[148:151], v[226:229], v[76:79]
	v_mfma_f32_16x16x32_bf16 v[72:75], v[160:163], v[226:229], v[72:75]
	s_setprio 0
	s_setprio 1
	v_mfma_f32_16x16x32_bf16 v[118:121], v[164:167], v[180:183], v[118:121]
	v_mfma_f32_16x16x32_bf16 v[114:117], v[172:175], v[180:183], v[114:117]
	v_mfma_f32_16x16x32_bf16 v[102:105], v[164:167], v[188:191], v[102:105]
	v_mfma_f32_16x16x32_bf16 v[98:101], v[172:175], v[188:191], v[98:101]
	v_mfma_f32_16x16x32_bf16 v[84:87], v[164:167], v[214:217], v[84:87]
	v_mfma_f32_16x16x32_bf16 v[80:83], v[172:175], v[214:217], v[80:83]
	v_mfma_f32_16x16x32_bf16 v[68:71], v[164:167], v[222:225], v[68:71]
	v_mfma_f32_16x16x32_bf16 v[64:67], v[172:175], v[222:225], v[64:67]
	v_mfma_f32_16x16x32_bf16 v[118:121], v[168:171], v[184:187], v[118:121]
	v_mfma_f32_16x16x32_bf16 v[114:117], v[176:179], v[184:187], v[114:117]
	v_mfma_f32_16x16x32_bf16 v[102:105], v[168:171], v[192:195], v[102:105]
	v_mfma_f32_16x16x32_bf16 v[98:101], v[176:179], v[192:195], v[98:101]
	v_mfma_f32_16x16x32_bf16 v[84:87], v[168:171], v[218:221], v[84:87]
	v_mfma_f32_16x16x32_bf16 v[80:83], v[176:179], v[218:221], v[80:83]
	v_mfma_f32_16x16x32_bf16 v[68:71], v[168:171], v[226:229], v[68:71]
	v_mfma_f32_16x16x32_bf16 v[64:67], v[176:179], v[226:229], v[64:67]
	s_setprio 0
	s_barrier
	s_add_i32 s28, s60, s39
	v_lshl_add_u64 v[156:157], v[156:157], 0, s[80:81]
	s_mov_b32 m0, s28
	s_nop 0
	global_load_lds_dwordx4 v[156:157], off
	v_lshl_add_u64 v[156:157], v[230:231], 0, s[80:81]
	s_add_i32 m0, s28, 0x2000
	s_add_i32 s28, s61, s39
	global_load_lds_dwordx4 v[156:157], off
	v_lshl_add_u64 v[156:157], v[232:233], 0, s[80:81]
	s_mov_b32 m0, s28
	s_nop 0
	global_load_lds_dwordx4 v[156:157], off
	v_lshl_add_u64 v[156:157], v[234:235], 0, s[80:81]
	s_add_i32 m0, s28, 0x2000
	s_nop 0
	global_load_lds_dwordx4 v[156:157], off
	v_lshl_add_u64 v[156:157], v[236:237], 0, s[80:81]
	s_mov_b32 m0, s51
	s_nop 0
	global_load_lds_dwordx4 v[156:157], off
	v_lshl_add_u64 v[156:157], v[238:239], 0, s[80:81]
	s_mov_b32 m0, s52
	s_nop 0
	global_load_lds_dwordx4 v[156:157], off
	ds_read_b128 v[180:183], v143 offset:49152
	ds_read_b128 v[184:187], v143 offset:50176
	ds_read_b128 v[188:191], v143 offset:51200
	ds_read_b128 v[192:195], v143 offset:52224
	ds_read_b128 v[214:217], v143 offset:53248
	ds_read_b128 v[218:221], v143 offset:54272
	ds_read_b128 v[222:225], v143 offset:55296
	ds_read_b128 v[226:229], v143 offset:56320
	s_waitcnt vmcnt(8)
	s_waitcnt lgkmcnt(0)
	s_barrier
	s_setprio 1
	s_waitcnt lgkmcnt(0)
	v_mfma_f32_16x16x32_bf16 v[60:63], v[144:147], v[180:183], v[60:63]
	v_mfma_f32_16x16x32_bf16 v[56:59], v[152:155], v[180:183], v[56:59]
	v_mfma_f32_16x16x32_bf16 v[44:47], v[144:147], v[188:191], v[44:47]
	v_mfma_f32_16x16x32_bf16 v[40:43], v[152:155], v[188:191], v[40:43]
	v_mfma_f32_16x16x32_bf16 v[28:31], v[144:147], v[214:217], v[28:31]
	v_mfma_f32_16x16x32_bf16 v[24:27], v[152:155], v[214:217], v[24:27]
	v_mfma_f32_16x16x32_bf16 v[12:15], v[144:147], v[222:225], v[12:15]
	v_mfma_f32_16x16x32_bf16 v[8:11], v[152:155], v[222:225], v[8:11]
	v_mfma_f32_16x16x32_bf16 v[60:63], v[148:151], v[184:187], v[60:63]
	v_mfma_f32_16x16x32_bf16 v[56:59], v[160:163], v[184:187], v[56:59]
	v_mfma_f32_16x16x32_bf16 v[44:47], v[148:151], v[192:195], v[44:47]
	v_mfma_f32_16x16x32_bf16 v[40:43], v[160:163], v[192:195], v[40:43]
	v_mfma_f32_16x16x32_bf16 v[28:31], v[148:151], v[218:221], v[28:31]
	v_mfma_f32_16x16x32_bf16 v[24:27], v[160:163], v[218:221], v[24:27]
	v_mfma_f32_16x16x32_bf16 v[12:15], v[148:151], v[226:229], v[12:15]
	v_mfma_f32_16x16x32_bf16 v[8:11], v[160:163], v[226:229], v[8:11]
	s_setprio 0
	s_setprio 1
	v_mfma_f32_16x16x32_bf16 v[52:55], v[164:167], v[180:183], v[52:55]
	v_mfma_f32_16x16x32_bf16 v[48:51], v[172:175], v[180:183], v[48:51]
	v_mfma_f32_16x16x32_bf16 v[36:39], v[164:167], v[188:191], v[36:39]
	v_mfma_f32_16x16x32_bf16 v[32:35], v[172:175], v[188:191], v[32:35]
	v_mfma_f32_16x16x32_bf16 v[20:23], v[164:167], v[214:217], v[20:23]
	v_mfma_f32_16x16x32_bf16 v[16:19], v[172:175], v[214:217], v[16:19]
	v_mfma_f32_16x16x32_bf16 v[4:7], v[164:167], v[222:225], v[4:7]
	v_mfma_f32_16x16x32_bf16 v[0:3], v[172:175], v[222:225], v[0:3]
	v_mfma_f32_16x16x32_bf16 v[52:55], v[168:171], v[184:187], v[52:55]
	v_mfma_f32_16x16x32_bf16 v[48:51], v[176:179], v[184:187], v[48:51]
	v_mfma_f32_16x16x32_bf16 v[36:39], v[168:171], v[192:195], v[36:39]
	v_mfma_f32_16x16x32_bf16 v[32:35], v[176:179], v[192:195], v[32:35]
	v_mfma_f32_16x16x32_bf16 v[20:23], v[168:171], v[218:221], v[20:23]
	v_mfma_f32_16x16x32_bf16 v[16:19], v[176:179], v[218:221], v[16:19]
	v_mfma_f32_16x16x32_bf16 v[4:7], v[168:171], v[226:229], v[4:7]
	v_mfma_f32_16x16x32_bf16 v[0:3], v[176:179], v[226:229], v[0:3]
	s_setprio 0
	s_barrier
	s_add_u32 s26, s26, 0x100
	s_addc_u32 s27, s27, 0
	s_add_u32 s57, s57, 0x100
	s_addc_u32 s58, s58, 0
	s_cmp_ge_i32 s59, s48
	s_mov_b32 s28, s59
	s_cbranch_scc0 .LBB0_1603

.LBB0_1749:
	s_add_i32 s59, s28, 2
	s_add_u32 s60, s6, 0x80
	s_addc_u32 s29, s7, 0
	s_add_i32 s62, 0, 0x10000
	s_cmp_eq_u32 s46, s28
	s_cselect_b32 s29, s25, s29
	s_cselect_b32 s28, s24, s60
	v_add_u32_e32 v157, s62, v155
	s_cselect_b32 s61, s27, s31
	s_cselect_b32 s60, s26, s30
	s_add_i32 s63, 0, 0x14000
	v_lshl_add_u64 v[234:235], s[6:7], 0, v[142:143]
	s_add_i32 m0, s38, 0xc000
	s_nop 0
	global_load_lds_dwordx4 v[234:235], off
	v_lshl_add_u64 v[234:235], s[6:7], 0, v[144:145]
	s_add_i32 m0, s38, 0xe000
	s_nop 0
	global_load_lds_dwordx4 v[234:235], off
	ds_read_b128 v[146:149], v157
	ds_read_b128 v[150:153], v157 offset:1024
	ds_read_b128 v[160:163], v157 offset:2048
	ds_read_b128 v[164:167], v157 offset:3072
	v_add_u32_e32 v157, s63, v155
	ds_read_b128 v[168:171], v157
	ds_read_b128 v[172:175], v157 offset:1024
	ds_read_b128 v[176:179], v157 offset:2048
	ds_read_b128 v[180:183], v157 offset:3072
	ds_read_b128 v[184:187], v156
	ds_read_b128 v[188:191], v156 offset:1024
	ds_read_b128 v[192:195], v156 offset:2048
	ds_read_b128 v[214:217], v156 offset:3072
	ds_read_b128 v[218:221], v156 offset:4096
	ds_read_b128 v[222:225], v156 offset:5120
	ds_read_b128 v[226:229], v156 offset:6144
	ds_read_b128 v[230:233], v156 offset:7168
	s_waitcnt vmcnt(8)
	s_waitcnt lgkmcnt(0)
	s_barrier
	s_setprio 1
	s_waitcnt lgkmcnt(0)
	v_mfma_f32_16x16x32_bf16 v[126:129], v[146:149], v[184:187], v[126:129]
	v_mfma_f32_16x16x32_bf16 v[122:125], v[160:163], v[184:187], v[122:125]
	v_mfma_f32_16x16x32_bf16 v[118:121], v[146:149], v[192:195], v[118:121]
	v_mfma_f32_16x16x32_bf16 v[114:117], v[160:163], v[192:195], v[114:117]
	v_mfma_f32_16x16x32_bf16 v[110:113], v[146:149], v[218:221], v[110:113]
	v_mfma_f32_16x16x32_bf16 v[106:109], v[160:163], v[218:221], v[106:109]
	v_mfma_f32_16x16x32_bf16 v[102:105], v[146:149], v[226:229], v[102:105]
	v_mfma_f32_16x16x32_bf16 v[98:101], v[160:163], v[226:229], v[98:101]
	v_mfma_f32_16x16x32_bf16 v[126:129], v[150:153], v[188:191], v[126:129]
	v_mfma_f32_16x16x32_bf16 v[122:125], v[164:167], v[188:191], v[122:125]
	v_mfma_f32_16x16x32_bf16 v[118:121], v[150:153], v[214:217], v[118:121]
	v_mfma_f32_16x16x32_bf16 v[114:117], v[164:167], v[214:217], v[114:117]
	v_mfma_f32_16x16x32_bf16 v[110:113], v[150:153], v[222:225], v[110:113]
	v_mfma_f32_16x16x32_bf16 v[106:109], v[164:167], v[222:225], v[106:109]
	v_mfma_f32_16x16x32_bf16 v[102:105], v[150:153], v[230:233], v[102:105]
	v_mfma_f32_16x16x32_bf16 v[98:101], v[164:167], v[230:233], v[98:101]
	s_setprio 0
	s_setprio 1
	v_mfma_f32_16x16x32_bf16 v[60:63], v[168:171], v[184:187], v[60:63]
	v_mfma_f32_16x16x32_bf16 v[56:59], v[176:179], v[184:187], v[56:59]
	v_mfma_f32_16x16x32_bf16 v[52:55], v[168:171], v[192:195], v[52:55]
	v_mfma_f32_16x16x32_bf16 v[48:51], v[176:179], v[192:195], v[48:51]
	v_mfma_f32_16x16x32_bf16 v[44:47], v[168:171], v[218:221], v[44:47]
	v_mfma_f32_16x16x32_bf16 v[40:43], v[176:179], v[218:221], v[40:43]
	v_mfma_f32_16x16x32_bf16 v[36:39], v[168:171], v[226:229], v[36:39]
	v_mfma_f32_16x16x32_bf16 v[32:35], v[176:179], v[226:229], v[32:35]
	v_mfma_f32_16x16x32_bf16 v[60:63], v[172:175], v[188:191], v[60:63]
	v_mfma_f32_16x16x32_bf16 v[56:59], v[180:183], v[188:191], v[56:59]
	v_mfma_f32_16x16x32_bf16 v[52:55], v[172:175], v[214:217], v[52:55]
	v_mfma_f32_16x16x32_bf16 v[48:51], v[180:183], v[214:217], v[48:51]
	v_mfma_f32_16x16x32_bf16 v[44:47], v[172:175], v[222:225], v[44:47]
	v_mfma_f32_16x16x32_bf16 v[40:43], v[180:183], v[222:225], v[40:43]
	v_mfma_f32_16x16x32_bf16 v[36:39], v[172:175], v[230:233], v[36:39]
	v_mfma_f32_16x16x32_bf16 v[32:35], v[180:183], v[230:233], v[32:35]
	s_setprio 0
	s_barrier
	s_add_i32 s62, s62, s37
	v_lshl_add_u64 v[234:235], s[60:61], 0, v[92:93]
	s_mov_b32 m0, s62
	s_nop 0
	global_load_lds_dwordx4 v[234:235], off
	s_add_i32 m0, s62, 0x2000
	v_lshl_add_u64 v[236:237], s[60:61], 0, v[134:135]
	s_add_u32 s60, s60, s8
	s_addc_u32 s61, s61, s9
	s_add_i32 s62, s63, s37
	global_load_lds_dwordx4 v[236:237], off
	v_lshl_add_u64 v[238:239], s[60:61], 0, v[92:93]
	s_mov_b32 m0, s62
	v_lshl_add_u64 v[240:241], s[60:61], 0, v[134:135]
	global_load_lds_dwordx4 v[238:239], off
	s_add_i32 m0, s62, 0x2000
	v_lshl_add_u64 v[242:243], s[28:29], 0, v[130:131]
	global_load_lds_dwordx4 v[240:241], off
	s_mov_b32 m0, s38
	v_lshl_add_u64 v[244:245], s[28:29], 0, v[132:133]
	global_load_lds_dwordx4 v[242:243], off
	s_mov_b32 m0, s39
	s_nop 0
	global_load_lds_dwordx4 v[244:245], off
	ds_read_b128 v[184:187], v156 offset:16384
	ds_read_b128 v[188:191], v156 offset:17408
	ds_read_b128 v[192:195], v156 offset:18432
	ds_read_b128 v[214:217], v156 offset:19456
	ds_read_b128 v[218:221], v156 offset:20480
	ds_read_b128 v[222:225], v156 offset:21504
	ds_read_b128 v[226:229], v156 offset:22528
	ds_read_b128 v[230:233], v156 offset:23552
	s_waitcnt vmcnt(8)
	s_waitcnt lgkmcnt(0)
	s_barrier
	s_setprio 1
	s_waitcnt lgkmcnt(0)
	v_mfma_f32_16x16x32_bf16 v[94:97], v[146:149], v[184:187], v[94:97]
	v_mfma_f32_16x16x32_bf16 v[88:91], v[160:163], v[184:187], v[88:91]
	v_mfma_f32_16x16x32_bf16 v[84:87], v[146:149], v[192:195], v[84:87]
	v_mfma_f32_16x16x32_bf16 v[80:83], v[160:163], v[192:195], v[80:83]
	v_mfma_f32_16x16x32_bf16 v[76:79], v[146:149], v[218:221], v[76:79]
	v_mfma_f32_16x16x32_bf16 v[72:75], v[160:163], v[218:221], v[72:75]
	v_mfma_f32_16x16x32_bf16 v[68:71], v[146:149], v[226:229], v[68:71]
	v_mfma_f32_16x16x32_bf16 v[64:67], v[160:163], v[226:229], v[64:67]
	v_mfma_f32_16x16x32_bf16 v[94:97], v[150:153], v[188:191], v[94:97]
	v_mfma_f32_16x16x32_bf16 v[88:91], v[164:167], v[188:191], v[88:91]
	v_mfma_f32_16x16x32_bf16 v[84:87], v[150:153], v[214:217], v[84:87]
	v_mfma_f32_16x16x32_bf16 v[80:83], v[164:167], v[214:217], v[80:83]
	v_mfma_f32_16x16x32_bf16 v[76:79], v[150:153], v[222:225], v[76:79]
	v_mfma_f32_16x16x32_bf16 v[72:75], v[164:167], v[222:225], v[72:75]
	v_mfma_f32_16x16x32_bf16 v[68:71], v[150:153], v[230:233], v[68:71]
	v_mfma_f32_16x16x32_bf16 v[64:67], v[164:167], v[230:233], v[64:67]
	s_setprio 0
	s_setprio 1
	v_mfma_f32_16x16x32_bf16 v[28:31], v[168:171], v[184:187], v[28:31]
	v_mfma_f32_16x16x32_bf16 v[24:27], v[176:179], v[184:187], v[24:27]
	v_mfma_f32_16x16x32_bf16 v[20:23], v[168:171], v[192:195], v[20:23]
	v_mfma_f32_16x16x32_bf16 v[16:19], v[176:179], v[192:195], v[16:19]
	v_mfma_f32_16x16x32_bf16 v[12:15], v[168:171], v[218:221], v[12:15]
	v_mfma_f32_16x16x32_bf16 v[8:11], v[176:179], v[218:221], v[8:11]
	v_mfma_f32_16x16x32_bf16 v[4:7], v[168:171], v[226:229], v[4:7]
	v_mfma_f32_16x16x32_bf16 v[0:3], v[176:179], v[226:229], v[0:3]
	v_mfma_f32_16x16x32_bf16 v[28:31], v[172:175], v[188:191], v[28:31]
	v_mfma_f32_16x16x32_bf16 v[24:27], v[180:183], v[188:191], v[24:27]
	v_mfma_f32_16x16x32_bf16 v[20:23], v[172:175], v[214:217], v[20:23]
	v_mfma_f32_16x16x32_bf16 v[16:19], v[180:183], v[214:217], v[16:19]
	v_mfma_f32_16x16x32_bf16 v[12:15], v[172:175], v[222:225], v[12:15]
	v_mfma_f32_16x16x32_bf16 v[8:11], v[180:183], v[222:225], v[8:11]
	v_mfma_f32_16x16x32_bf16 v[4:7], v[172:175], v[230:233], v[4:7]
	v_mfma_f32_16x16x32_bf16 v[0:3], v[180:183], v[230:233], v[0:3]
	s_setprio 0
	s_barrier
	s_add_i32 s60, 0, 0x18000
	v_add_u32_e32 v157, s60, v155
	s_add_i32 s61, 0, 0x1c000
	s_add_u32 s28, s28, s12
	s_addc_u32 s29, s29, s13
	s_mov_b32 m0, s40
	v_lshl_add_u64 v[246:247], s[28:29], 0, v[130:131]
	global_load_lds_dwordx4 v[246:247], off
	v_lshl_add_u64 v[246:247], s[28:29], 0, v[132:133]
	s_mov_b32 m0, s41
	s_nop 0
	global_load_lds_dwordx4 v[246:247], off
	ds_read_b128 v[146:149], v157
	ds_read_b128 v[150:153], v157 offset:1024
	ds_read_b128 v[160:163], v157 offset:2048
	ds_read_b128 v[164:167], v157 offset:3072
	v_add_u32_e32 v157, s61, v155
	ds_read_b128 v[168:171], v157
	ds_read_b128 v[172:175], v157 offset:1024
	ds_read_b128 v[176:179], v157 offset:2048
	ds_read_b128 v[180:183], v157 offset:3072
	ds_read_b128 v[184:187], v156 offset:32768
	ds_read_b128 v[188:191], v156 offset:33792
	ds_read_b128 v[192:195], v156 offset:34816
	ds_read_b128 v[214:217], v156 offset:35840
	ds_read_b128 v[218:221], v156 offset:36864
	ds_read_b128 v[222:225], v156 offset:37888
	ds_read_b128 v[226:229], v156 offset:38912
	ds_read_b128 v[230:233], v156 offset:39936
	s_waitcnt vmcnt(8)
	s_waitcnt lgkmcnt(0)
	s_barrier
	s_setprio 1
	s_waitcnt lgkmcnt(0)
	v_mfma_f32_16x16x32_bf16 v[126:129], v[146:149], v[184:187], v[126:129]
	v_mfma_f32_16x16x32_bf16 v[122:125], v[160:163], v[184:187], v[122:125]
	v_mfma_f32_16x16x32_bf16 v[118:121], v[146:149], v[192:195], v[118:121]
	v_mfma_f32_16x16x32_bf16 v[114:117], v[160:163], v[192:195], v[114:117]
	v_mfma_f32_16x16x32_bf16 v[110:113], v[146:149], v[218:221], v[110:113]
	v_mfma_f32_16x16x32_bf16 v[106:109], v[160:163], v[218:221], v[106:109]
	v_mfma_f32_16x16x32_bf16 v[102:105], v[146:149], v[226:229], v[102:105]
	v_mfma_f32_16x16x32_bf16 v[98:101], v[160:163], v[226:229], v[98:101]
	v_mfma_f32_16x16x32_bf16 v[126:129], v[150:153], v[188:191], v[126:129]
	v_mfma_f32_16x16x32_bf16 v[122:125], v[164:167], v[188:191], v[122:125]
	v_mfma_f32_16x16x32_bf16 v[118:121], v[150:153], v[214:217], v[118:121]
	v_mfma_f32_16x16x32_bf16 v[114:117], v[164:167], v[214:217], v[114:117]
	v_mfma_f32_16x16x32_bf16 v[110:113], v[150:153], v[222:225], v[110:113]
	v_mfma_f32_16x16x32_bf16 v[106:109], v[164:167], v[222:225], v[106:109]
	v_mfma_f32_16x16x32_bf16 v[102:105], v[150:153], v[230:233], v[102:105]
	v_mfma_f32_16x16x32_bf16 v[98:101], v[164:167], v[230:233], v[98:101]
	s_setprio 0
	s_setprio 1
	v_mfma_f32_16x16x32_bf16 v[60:63], v[168:171], v[184:187], v[60:63]
	v_mfma_f32_16x16x32_bf16 v[56:59], v[176:179], v[184:187], v[56:59]
	v_mfma_f32_16x16x32_bf16 v[52:55], v[168:171], v[192:195], v[52:55]
	v_mfma_f32_16x16x32_bf16 v[48:51], v[176:179], v[192:195], v[48:51]
	v_mfma_f32_16x16x32_bf16 v[44:47], v[168:171], v[218:221], v[44:47]
	v_mfma_f32_16x16x32_bf16 v[40:43], v[176:179], v[218:221], v[40:43]
	v_mfma_f32_16x16x32_bf16 v[36:39], v[168:171], v[226:229], v[36:39]
	v_mfma_f32_16x16x32_bf16 v[32:35], v[176:179], v[226:229], v[32:35]
	v_mfma_f32_16x16x32_bf16 v[60:63], v[172:175], v[188:191], v[60:63]
	v_mfma_f32_16x16x32_bf16 v[56:59], v[180:183], v[188:191], v[56:59]
	v_mfma_f32_16x16x32_bf16 v[52:55], v[172:175], v[214:217], v[52:55]
	v_mfma_f32_16x16x32_bf16 v[48:51], v[180:183], v[214:217], v[48:51]
	v_mfma_f32_16x16x32_bf16 v[44:47], v[172:175], v[222:225], v[44:47]
	v_mfma_f32_16x16x32_bf16 v[40:43], v[180:183], v[222:225], v[40:43]
	v_mfma_f32_16x16x32_bf16 v[36:39], v[172:175], v[230:233], v[36:39]
	v_mfma_f32_16x16x32_bf16 v[32:35], v[180:183], v[230:233], v[32:35]
	s_setprio 0
	s_barrier
	s_add_i32 s28, s60, s37
	v_lshl_add_u64 v[234:235], v[234:235], 0, s[80:81]
	s_mov_b32 m0, s28
	s_nop 0
	global_load_lds_dwordx4 v[234:235], off
	v_lshl_add_u64 v[234:235], v[236:237], 0, s[80:81]
	s_add_i32 m0, s28, 0x2000
	s_add_i32 s28, s61, s37
	global_load_lds_dwordx4 v[234:235], off
	v_lshl_add_u64 v[234:235], v[238:239], 0, s[80:81]
	s_mov_b32 m0, s28
	s_nop 0
	global_load_lds_dwordx4 v[234:235], off
	v_lshl_add_u64 v[234:235], v[240:241], 0, s[80:81]
	s_add_i32 m0, s28, 0x2000
	s_nop 0
	global_load_lds_dwordx4 v[234:235], off
	v_lshl_add_u64 v[234:235], v[242:243], 0, s[80:81]
	s_mov_b32 m0, s42
	s_nop 0
	global_load_lds_dwordx4 v[234:235], off
	v_lshl_add_u64 v[234:235], v[244:245], 0, s[80:81]
	s_mov_b32 m0, s43
	s_nop 0
	global_load_lds_dwordx4 v[234:235], off
	ds_read_b128 v[184:187], v156 offset:49152
	ds_read_b128 v[188:191], v156 offset:50176
	ds_read_b128 v[192:195], v156 offset:51200
	ds_read_b128 v[214:217], v156 offset:52224
	ds_read_b128 v[218:221], v156 offset:53248
	ds_read_b128 v[222:225], v156 offset:54272
	ds_read_b128 v[226:229], v156 offset:55296
	ds_read_b128 v[230:233], v156 offset:56320
	s_waitcnt vmcnt(8)
	s_waitcnt lgkmcnt(0)
	s_barrier
	s_setprio 1
	s_waitcnt lgkmcnt(0)
	v_mfma_f32_16x16x32_bf16 v[94:97], v[146:149], v[184:187], v[94:97]
	v_mfma_f32_16x16x32_bf16 v[88:91], v[160:163], v[184:187], v[88:91]
	v_mfma_f32_16x16x32_bf16 v[84:87], v[146:149], v[192:195], v[84:87]
	v_mfma_f32_16x16x32_bf16 v[80:83], v[160:163], v[192:195], v[80:83]
	v_mfma_f32_16x16x32_bf16 v[76:79], v[146:149], v[218:221], v[76:79]
	v_mfma_f32_16x16x32_bf16 v[72:75], v[160:163], v[218:221], v[72:75]
	v_mfma_f32_16x16x32_bf16 v[68:71], v[146:149], v[226:229], v[68:71]
	v_mfma_f32_16x16x32_bf16 v[64:67], v[160:163], v[226:229], v[64:67]
	v_mfma_f32_16x16x32_bf16 v[94:97], v[150:153], v[188:191], v[94:97]
	v_mfma_f32_16x16x32_bf16 v[88:91], v[164:167], v[188:191], v[88:91]
	v_mfma_f32_16x16x32_bf16 v[84:87], v[150:153], v[214:217], v[84:87]
	v_mfma_f32_16x16x32_bf16 v[80:83], v[164:167], v[214:217], v[80:83]
	v_mfma_f32_16x16x32_bf16 v[76:79], v[150:153], v[222:225], v[76:79]
	v_mfma_f32_16x16x32_bf16 v[72:75], v[164:167], v[222:225], v[72:75]
	v_mfma_f32_16x16x32_bf16 v[68:71], v[150:153], v[230:233], v[68:71]
	v_mfma_f32_16x16x32_bf16 v[64:67], v[164:167], v[230:233], v[64:67]
	s_setprio 0
	s_setprio 1
	v_mfma_f32_16x16x32_bf16 v[28:31], v[168:171], v[184:187], v[28:31]
	v_mfma_f32_16x16x32_bf16 v[24:27], v[176:179], v[184:187], v[24:27]
	v_mfma_f32_16x16x32_bf16 v[20:23], v[168:171], v[192:195], v[20:23]
	v_mfma_f32_16x16x32_bf16 v[16:19], v[176:179], v[192:195], v[16:19]
	v_mfma_f32_16x16x32_bf16 v[12:15], v[168:171], v[218:221], v[12:15]
	v_mfma_f32_16x16x32_bf16 v[8:11], v[176:179], v[218:221], v[8:11]
	v_mfma_f32_16x16x32_bf16 v[4:7], v[168:171], v[226:229], v[4:7]
	v_mfma_f32_16x16x32_bf16 v[0:3], v[176:179], v[226:229], v[0:3]
	v_mfma_f32_16x16x32_bf16 v[28:31], v[172:175], v[188:191], v[28:31]
	v_mfma_f32_16x16x32_bf16 v[24:27], v[180:183], v[188:191], v[24:27]
	v_mfma_f32_16x16x32_bf16 v[20:23], v[172:175], v[214:217], v[20:23]
	v_mfma_f32_16x16x32_bf16 v[16:19], v[180:183], v[214:217], v[16:19]
	v_mfma_f32_16x16x32_bf16 v[12:15], v[172:175], v[222:225], v[12:15]
	v_mfma_f32_16x16x32_bf16 v[8:11], v[180:183], v[222:225], v[8:11]
	v_mfma_f32_16x16x32_bf16 v[4:7], v[172:175], v[230:233], v[4:7]
	v_mfma_f32_16x16x32_bf16 v[0:3], v[180:183], v[230:233], v[0:3]
	s_setprio 0
	s_barrier
	s_add_u32 s6, s6, 0x100
	s_addc_u32 s7, s7, 0
	s_add_u32 s30, s30, 0x100
	s_addc_u32 s31, s31, 0
	s_cmp_ge_i32 s59, s44
	s_mov_b32 s28, s59
	s_cbranch_scc0 .LBB0_1749

.LBB0_1812:
	s_add_i32 s60, s30, 2
	s_add_u32 s61, s6, 0x80
	s_addc_u32 s31, s7, 0
	s_add_i32 s64, 0, 0x10000
	s_cmp_eq_u32 s47, s30
	s_cselect_b32 s31, s27, s31
	s_cselect_b32 s30, s26, s61
	v_add_u32_e32 v92, s64, v150
	s_cselect_b32 s63, s29, s35
	s_cselect_b32 s62, s28, s34
	s_add_i32 s61, 0, 0x14000
	v_lshl_add_u64 v[156:157], s[6:7], 0, v[142:143]
	s_add_i32 m0, s40, 0xc000
	s_nop 0
	global_load_lds_dwordx4 v[156:157], off
	v_lshl_add_u64 v[156:157], s[6:7], 0, v[144:145]
	s_add_i32 m0, s40, 0xe000
	s_nop 0
	global_load_lds_dwordx4 v[156:157], off
	ds_read_b128 v[146:149], v92
	ds_read_b128 v[152:155], v92 offset:1024
	ds_read_b128 v[160:163], v92 offset:2048
	ds_read_b128 v[164:167], v92 offset:3072
	v_add_u32_e32 v92, s61, v150
	ds_read_b128 v[168:171], v92
	ds_read_b128 v[172:175], v92 offset:1024
	ds_read_b128 v[176:179], v92 offset:2048
	ds_read_b128 v[180:183], v92 offset:3072
	ds_read_b128 v[184:187], v151
	ds_read_b128 v[188:191], v151 offset:1024
	ds_read_b128 v[192:195], v151 offset:2048
	ds_read_b128 v[214:217], v151 offset:3072
	ds_read_b128 v[218:221], v151 offset:4096
	ds_read_b128 v[222:225], v151 offset:5120
	ds_read_b128 v[226:229], v151 offset:6144
	ds_read_b128 v[230:233], v151 offset:7168
	s_waitcnt vmcnt(8)
	s_waitcnt lgkmcnt(0)
	s_barrier
	s_setprio 1
	s_waitcnt lgkmcnt(0)
	v_mfma_f32_16x16x32_bf16 v[126:129], v[146:149], v[184:187], v[126:129]
	v_mfma_f32_16x16x32_bf16 v[122:125], v[160:163], v[184:187], v[122:125]
	v_mfma_f32_16x16x32_bf16 v[118:121], v[146:149], v[192:195], v[118:121]
	v_mfma_f32_16x16x32_bf16 v[114:117], v[160:163], v[192:195], v[114:117]
	v_mfma_f32_16x16x32_bf16 v[110:113], v[146:149], v[218:221], v[110:113]
	v_mfma_f32_16x16x32_bf16 v[106:109], v[160:163], v[218:221], v[106:109]
	v_mfma_f32_16x16x32_bf16 v[102:105], v[146:149], v[226:229], v[102:105]
	v_mfma_f32_16x16x32_bf16 v[98:101], v[160:163], v[226:229], v[98:101]
	v_mfma_f32_16x16x32_bf16 v[126:129], v[152:155], v[188:191], v[126:129]
	v_mfma_f32_16x16x32_bf16 v[122:125], v[164:167], v[188:191], v[122:125]
	v_mfma_f32_16x16x32_bf16 v[118:121], v[152:155], v[214:217], v[118:121]
	v_mfma_f32_16x16x32_bf16 v[114:117], v[164:167], v[214:217], v[114:117]
	v_mfma_f32_16x16x32_bf16 v[110:113], v[152:155], v[222:225], v[110:113]
	v_mfma_f32_16x16x32_bf16 v[106:109], v[164:167], v[222:225], v[106:109]
	v_mfma_f32_16x16x32_bf16 v[102:105], v[152:155], v[230:233], v[102:105]
	v_mfma_f32_16x16x32_bf16 v[98:101], v[164:167], v[230:233], v[98:101]
	s_setprio 0
	s_setprio 1
	v_mfma_f32_16x16x32_bf16 v[60:63], v[168:171], v[184:187], v[60:63]
	v_mfma_f32_16x16x32_bf16 v[56:59], v[176:179], v[184:187], v[56:59]
	v_mfma_f32_16x16x32_bf16 v[52:55], v[168:171], v[192:195], v[52:55]
	v_mfma_f32_16x16x32_bf16 v[48:51], v[176:179], v[192:195], v[48:51]
	v_mfma_f32_16x16x32_bf16 v[44:47], v[168:171], v[218:221], v[44:47]
	v_mfma_f32_16x16x32_bf16 v[40:43], v[176:179], v[218:221], v[40:43]
	v_mfma_f32_16x16x32_bf16 v[36:39], v[168:171], v[226:229], v[36:39]
	v_mfma_f32_16x16x32_bf16 v[32:35], v[176:179], v[226:229], v[32:35]
	v_mfma_f32_16x16x32_bf16 v[60:63], v[172:175], v[188:191], v[60:63]
	v_mfma_f32_16x16x32_bf16 v[56:59], v[180:183], v[188:191], v[56:59]
	v_mfma_f32_16x16x32_bf16 v[52:55], v[172:175], v[214:217], v[52:55]
	v_mfma_f32_16x16x32_bf16 v[48:51], v[180:183], v[214:217], v[48:51]
	v_mfma_f32_16x16x32_bf16 v[44:47], v[172:175], v[222:225], v[44:47]
	v_mfma_f32_16x16x32_bf16 v[40:43], v[180:183], v[222:225], v[40:43]
	v_mfma_f32_16x16x32_bf16 v[36:39], v[172:175], v[230:233], v[36:39]
	v_mfma_f32_16x16x32_bf16 v[32:35], v[180:183], v[230:233], v[32:35]
	s_setprio 0
	s_barrier
	s_add_i32 s64, s64, s39
	v_lshl_add_u64 v[156:157], s[62:63], 0, v[132:133]
	s_mov_b32 m0, s64
	s_nop 0
	global_load_lds_dwordx4 v[156:157], off
	s_add_i32 m0, s64, 0x2000
	v_lshl_add_u64 v[234:235], s[62:63], 0, v[136:137]
	s_add_u32 s62, s62, s8
	s_addc_u32 s63, s63, s9
	s_add_i32 s61, s61, s39
	global_load_lds_dwordx4 v[234:235], off
	v_lshl_add_u64 v[236:237], s[62:63], 0, v[132:133]
	s_mov_b32 m0, s61
	v_lshl_add_u64 v[238:239], s[62:63], 0, v[136:137]
	global_load_lds_dwordx4 v[236:237], off
	s_add_i32 m0, s61, 0x2000
	v_lshl_add_u64 v[240:241], s[30:31], 0, v[130:131]
	global_load_lds_dwordx4 v[238:239], off
	s_mov_b32 m0, s40
	v_lshl_add_u64 v[242:243], s[30:31], 0, v[134:135]
	global_load_lds_dwordx4 v[240:241], off
	s_mov_b32 m0, s41
	s_nop 0
	global_load_lds_dwordx4 v[242:243], off
	ds_read_b128 v[184:187], v151 offset:16384
	ds_read_b128 v[188:191], v151 offset:17408
	ds_read_b128 v[192:195], v151 offset:18432
	ds_read_b128 v[214:217], v151 offset:19456
	ds_read_b128 v[218:221], v151 offset:20480
	ds_read_b128 v[222:225], v151 offset:21504
	ds_read_b128 v[226:229], v151 offset:22528
	ds_read_b128 v[230:233], v151 offset:23552
	s_waitcnt vmcnt(8)
	s_waitcnt lgkmcnt(0)
	s_barrier
	s_setprio 1
	s_waitcnt lgkmcnt(0)
	v_mfma_f32_16x16x32_bf16 v[94:97], v[146:149], v[184:187], v[94:97]
	v_mfma_f32_16x16x32_bf16 v[88:91], v[160:163], v[184:187], v[88:91]
	v_mfma_f32_16x16x32_bf16 v[84:87], v[146:149], v[192:195], v[84:87]
	v_mfma_f32_16x16x32_bf16 v[80:83], v[160:163], v[192:195], v[80:83]
	v_mfma_f32_16x16x32_bf16 v[76:79], v[146:149], v[218:221], v[76:79]
	v_mfma_f32_16x16x32_bf16 v[72:75], v[160:163], v[218:221], v[72:75]
	v_mfma_f32_16x16x32_bf16 v[68:71], v[146:149], v[226:229], v[68:71]
	v_mfma_f32_16x16x32_bf16 v[64:67], v[160:163], v[226:229], v[64:67]
	v_mfma_f32_16x16x32_bf16 v[94:97], v[152:155], v[188:191], v[94:97]
	v_mfma_f32_16x16x32_bf16 v[88:91], v[164:167], v[188:191], v[88:91]
	v_mfma_f32_16x16x32_bf16 v[84:87], v[152:155], v[214:217], v[84:87]
	v_mfma_f32_16x16x32_bf16 v[80:83], v[164:167], v[214:217], v[80:83]
	v_mfma_f32_16x16x32_bf16 v[76:79], v[152:155], v[222:225], v[76:79]
	v_mfma_f32_16x16x32_bf16 v[72:75], v[164:167], v[222:225], v[72:75]
	v_mfma_f32_16x16x32_bf16 v[68:71], v[152:155], v[230:233], v[68:71]
	v_mfma_f32_16x16x32_bf16 v[64:67], v[164:167], v[230:233], v[64:67]
	s_setprio 0
	s_setprio 1
	v_mfma_f32_16x16x32_bf16 v[28:31], v[168:171], v[184:187], v[28:31]
	v_mfma_f32_16x16x32_bf16 v[24:27], v[176:179], v[184:187], v[24:27]
	v_mfma_f32_16x16x32_bf16 v[20:23], v[168:171], v[192:195], v[20:23]
	v_mfma_f32_16x16x32_bf16 v[16:19], v[176:179], v[192:195], v[16:19]
	v_mfma_f32_16x16x32_bf16 v[12:15], v[168:171], v[218:221], v[12:15]
	v_mfma_f32_16x16x32_bf16 v[8:11], v[176:179], v[218:221], v[8:11]
	v_mfma_f32_16x16x32_bf16 v[4:7], v[168:171], v[226:229], v[4:7]
	v_mfma_f32_16x16x32_bf16 v[0:3], v[176:179], v[226:229], v[0:3]
	v_mfma_f32_16x16x32_bf16 v[28:31], v[172:175], v[188:191], v[28:31]
	v_mfma_f32_16x16x32_bf16 v[24:27], v[180:183], v[188:191], v[24:27]
	v_mfma_f32_16x16x32_bf16 v[20:23], v[172:175], v[214:217], v[20:23]
	v_mfma_f32_16x16x32_bf16 v[16:19], v[180:183], v[214:217], v[16:19]
	v_mfma_f32_16x16x32_bf16 v[12:15], v[172:175], v[222:225], v[12:15]
	v_mfma_f32_16x16x32_bf16 v[8:11], v[180:183], v[222:225], v[8:11]
	v_mfma_f32_16x16x32_bf16 v[4:7], v[172:175], v[230:233], v[4:7]
	v_mfma_f32_16x16x32_bf16 v[0:3], v[180:183], v[230:233], v[0:3]
	s_setprio 0
	s_barrier
	s_add_i32 s61, 0, 0x18000
	v_add_u32_e32 v92, s61, v150
	s_add_i32 s62, 0, 0x1c000
	s_add_u32 s30, s30, s12
	s_addc_u32 s31, s31, s13
	s_mov_b32 m0, s42
	v_lshl_add_u64 v[244:245], s[30:31], 0, v[130:131]
	global_load_lds_dwordx4 v[244:245], off
	v_lshl_add_u64 v[244:245], s[30:31], 0, v[134:135]
	s_mov_b32 m0, s43
	s_nop 0
	global_load_lds_dwordx4 v[244:245], off
	ds_read_b128 v[146:149], v92
	ds_read_b128 v[152:155], v92 offset:1024
	ds_read_b128 v[160:163], v92 offset:2048
	ds_read_b128 v[164:167], v92 offset:3072
	v_add_u32_e32 v92, s62, v150
	ds_read_b128 v[168:171], v92
	ds_read_b128 v[172:175], v92 offset:1024
	ds_read_b128 v[176:179], v92 offset:2048
	ds_read_b128 v[180:183], v92 offset:3072
	ds_read_b128 v[184:187], v151 offset:32768
	ds_read_b128 v[188:191], v151 offset:33792
	ds_read_b128 v[192:195], v151 offset:34816
	ds_read_b128 v[214:217], v151 offset:35840
	ds_read_b128 v[218:221], v151 offset:36864
	ds_read_b128 v[222:225], v151 offset:37888
	ds_read_b128 v[226:229], v151 offset:38912
	ds_read_b128 v[230:233], v151 offset:39936
	s_waitcnt vmcnt(8)
	s_waitcnt lgkmcnt(0)
	s_barrier
	s_setprio 1
	s_waitcnt lgkmcnt(0)
	v_mfma_f32_16x16x32_bf16 v[126:129], v[146:149], v[184:187], v[126:129]
	v_mfma_f32_16x16x32_bf16 v[122:125], v[160:163], v[184:187], v[122:125]
	v_mfma_f32_16x16x32_bf16 v[118:121], v[146:149], v[192:195], v[118:121]
	v_mfma_f32_16x16x32_bf16 v[114:117], v[160:163], v[192:195], v[114:117]
	v_mfma_f32_16x16x32_bf16 v[110:113], v[146:149], v[218:221], v[110:113]
	v_mfma_f32_16x16x32_bf16 v[106:109], v[160:163], v[218:221], v[106:109]
	v_mfma_f32_16x16x32_bf16 v[102:105], v[146:149], v[226:229], v[102:105]
	v_mfma_f32_16x16x32_bf16 v[98:101], v[160:163], v[226:229], v[98:101]
	v_mfma_f32_16x16x32_bf16 v[126:129], v[152:155], v[188:191], v[126:129]
	v_mfma_f32_16x16x32_bf16 v[122:125], v[164:167], v[188:191], v[122:125]
	v_mfma_f32_16x16x32_bf16 v[118:121], v[152:155], v[214:217], v[118:121]
	v_mfma_f32_16x16x32_bf16 v[114:117], v[164:167], v[214:217], v[114:117]
	v_mfma_f32_16x16x32_bf16 v[110:113], v[152:155], v[222:225], v[110:113]
	v_mfma_f32_16x16x32_bf16 v[106:109], v[164:167], v[222:225], v[106:109]
	v_mfma_f32_16x16x32_bf16 v[102:105], v[152:155], v[230:233], v[102:105]
	v_mfma_f32_16x16x32_bf16 v[98:101], v[164:167], v[230:233], v[98:101]
	s_setprio 0
	s_setprio 1
	v_mfma_f32_16x16x32_bf16 v[60:63], v[168:171], v[184:187], v[60:63]
	v_mfma_f32_16x16x32_bf16 v[56:59], v[176:179], v[184:187], v[56:59]
	v_mfma_f32_16x16x32_bf16 v[52:55], v[168:171], v[192:195], v[52:55]
	v_mfma_f32_16x16x32_bf16 v[48:51], v[176:179], v[192:195], v[48:51]
	v_mfma_f32_16x16x32_bf16 v[44:47], v[168:171], v[218:221], v[44:47]
	v_mfma_f32_16x16x32_bf16 v[40:43], v[176:179], v[218:221], v[40:43]
	v_mfma_f32_16x16x32_bf16 v[36:39], v[168:171], v[226:229], v[36:39]
	v_mfma_f32_16x16x32_bf16 v[32:35], v[176:179], v[226:229], v[32:35]
	v_mfma_f32_16x16x32_bf16 v[60:63], v[172:175], v[188:191], v[60:63]
	v_mfma_f32_16x16x32_bf16 v[56:59], v[180:183], v[188:191], v[56:59]
	v_mfma_f32_16x16x32_bf16 v[52:55], v[172:175], v[214:217], v[52:55]
	v_mfma_f32_16x16x32_bf16 v[48:51], v[180:183], v[214:217], v[48:51]
	v_mfma_f32_16x16x32_bf16 v[44:47], v[172:175], v[222:225], v[44:47]
	v_mfma_f32_16x16x32_bf16 v[40:43], v[180:183], v[222:225], v[40:43]
	v_mfma_f32_16x16x32_bf16 v[36:39], v[172:175], v[230:233], v[36:39]
	v_mfma_f32_16x16x32_bf16 v[32:35], v[180:183], v[230:233], v[32:35]
	s_setprio 0
	s_barrier
	s_add_i32 s30, s61, s39
	v_lshl_add_u64 v[156:157], v[156:157], 0, s[80:81]
	s_mov_b32 m0, s30
	s_nop 0
	global_load_lds_dwordx4 v[156:157], off
	v_lshl_add_u64 v[156:157], v[234:235], 0, s[80:81]
	s_add_i32 m0, s30, 0x2000
	s_add_i32 s30, s62, s39
	global_load_lds_dwordx4 v[156:157], off
	v_lshl_add_u64 v[156:157], v[236:237], 0, s[80:81]
	s_mov_b32 m0, s30
	s_nop 0
	global_load_lds_dwordx4 v[156:157], off
	v_lshl_add_u64 v[156:157], v[238:239], 0, s[80:81]
	s_add_i32 m0, s30, 0x2000
	s_nop 0
	global_load_lds_dwordx4 v[156:157], off
	v_lshl_add_u64 v[156:157], v[240:241], 0, s[80:81]
	s_mov_b32 m0, s45
	s_nop 0
	global_load_lds_dwordx4 v[156:157], off
	v_lshl_add_u64 v[156:157], v[242:243], 0, s[80:81]
	s_mov_b32 m0, s46
	s_nop 0
	global_load_lds_dwordx4 v[156:157], off
	ds_read_b128 v[184:187], v151 offset:49152
	ds_read_b128 v[188:191], v151 offset:50176
	ds_read_b128 v[192:195], v151 offset:51200
	ds_read_b128 v[214:217], v151 offset:52224
	ds_read_b128 v[218:221], v151 offset:53248
	ds_read_b128 v[222:225], v151 offset:54272
	ds_read_b128 v[226:229], v151 offset:55296
	ds_read_b128 v[230:233], v151 offset:56320
	s_waitcnt vmcnt(8)
	s_waitcnt lgkmcnt(0)
	s_barrier
	s_setprio 1
	s_waitcnt lgkmcnt(0)
	v_mfma_f32_16x16x32_bf16 v[94:97], v[146:149], v[184:187], v[94:97]
	v_mfma_f32_16x16x32_bf16 v[88:91], v[160:163], v[184:187], v[88:91]
	v_mfma_f32_16x16x32_bf16 v[84:87], v[146:149], v[192:195], v[84:87]
	v_mfma_f32_16x16x32_bf16 v[80:83], v[160:163], v[192:195], v[80:83]
	v_mfma_f32_16x16x32_bf16 v[76:79], v[146:149], v[218:221], v[76:79]
	v_mfma_f32_16x16x32_bf16 v[72:75], v[160:163], v[218:221], v[72:75]
	v_mfma_f32_16x16x32_bf16 v[68:71], v[146:149], v[226:229], v[68:71]
	v_mfma_f32_16x16x32_bf16 v[64:67], v[160:163], v[226:229], v[64:67]
	v_mfma_f32_16x16x32_bf16 v[94:97], v[152:155], v[188:191], v[94:97]
	v_mfma_f32_16x16x32_bf16 v[88:91], v[164:167], v[188:191], v[88:91]
	v_mfma_f32_16x16x32_bf16 v[84:87], v[152:155], v[214:217], v[84:87]
	v_mfma_f32_16x16x32_bf16 v[80:83], v[164:167], v[214:217], v[80:83]
	v_mfma_f32_16x16x32_bf16 v[76:79], v[152:155], v[222:225], v[76:79]
	v_mfma_f32_16x16x32_bf16 v[72:75], v[164:167], v[222:225], v[72:75]
	v_mfma_f32_16x16x32_bf16 v[68:71], v[152:155], v[230:233], v[68:71]
	v_mfma_f32_16x16x32_bf16 v[64:67], v[164:167], v[230:233], v[64:67]
	s_setprio 0
	s_setprio 1
	v_mfma_f32_16x16x32_bf16 v[28:31], v[168:171], v[184:187], v[28:31]
	v_mfma_f32_16x16x32_bf16 v[24:27], v[176:179], v[184:187], v[24:27]
	v_mfma_f32_16x16x32_bf16 v[20:23], v[168:171], v[192:195], v[20:23]
	v_mfma_f32_16x16x32_bf16 v[16:19], v[176:179], v[192:195], v[16:19]
	v_mfma_f32_16x16x32_bf16 v[12:15], v[168:171], v[218:221], v[12:15]
	v_mfma_f32_16x16x32_bf16 v[8:11], v[176:179], v[218:221], v[8:11]
	v_mfma_f32_16x16x32_bf16 v[4:7], v[168:171], v[226:229], v[4:7]
	v_mfma_f32_16x16x32_bf16 v[0:3], v[176:179], v[226:229], v[0:3]
	v_mfma_f32_16x16x32_bf16 v[28:31], v[172:175], v[188:191], v[28:31]
	v_mfma_f32_16x16x32_bf16 v[24:27], v[180:183], v[188:191], v[24:27]
	v_mfma_f32_16x16x32_bf16 v[20:23], v[172:175], v[214:217], v[20:23]
	v_mfma_f32_16x16x32_bf16 v[16:19], v[180:183], v[214:217], v[16:19]
	v_mfma_f32_16x16x32_bf16 v[12:15], v[172:175], v[222:225], v[12:15]
	v_mfma_f32_16x16x32_bf16 v[8:11], v[180:183], v[222:225], v[8:11]
	v_mfma_f32_16x16x32_bf16 v[4:7], v[172:175], v[230:233], v[4:7]
	v_mfma_f32_16x16x32_bf16 v[0:3], v[180:183], v[230:233], v[0:3]
	s_setprio 0
	s_barrier
	s_add_u32 s6, s6, 0x100
	s_addc_u32 s7, s7, 0
	s_add_u32 s34, s34, 0x100
	s_addc_u32 s35, s35, 0
	s_cmp_ge_i32 s60, s44
	s_mov_b32 s30, s60
	s_cbranch_scc0 .LBB0_1812
